# GEMM K-loops: s_setprio 1 moved in front of the after-load barrier, duplicate lgkmcnt(0) behind it removed, s_setprio 0 moved behind the after-MFMA barrier
# speedup vs baseline: 1.0089x; 1.0043x over previous
; #define PG8_STAGE(bufoff, gbase, voff) do { _Pragma("unroll") for (int _i = 0; _i < 2; ++_i) \
;         __builtin_amdgcn_global_load_lds((const unsigned*)((const char*)(gbase) + (voff)[_i]), (PG8_LAS unsigned*)(lds + (bufoff) + ldsw + _i * 8192), 16, 0, 0); } while (0)
; #define PG8_LDA(dst, b, h) do { _Pragma("unroll") for (int m = 0; m < 4; ++m) _Pragma("unroll") for (int k = 0; k < 2; ++k) dst[m][k] = *(const PG8_LAS bf16x8*)(lds + PG8_SA(b, h) + aoff + m * 2048 + k * 1024); } while (0)
; #define PG8_LDB(dst, b, h) do { _Pragma("unroll") for (int n = 0; n < 2; ++n) _Pragma("unroll") for (int k = 0; k < 2; ++k) dst[n][k] = *(const PG8_LAS bf16x8*)(lds + PG8_SB(b, h) + boff + n * 2048 + k * 1024); } while (0)
; #define PG8_MMA(ai, bj, At, Bt) do { __builtin_amdgcn_s_setprio(1); _Pragma("unroll") for (int m = 0; m < 4; ++m) _Pragma("unroll") for (int n = 0; n < 2; ++n) _Pragma("unroll") for (int k = 0; k < 2; ++k) \
;         acc[ai][bj][m][n] = __builtin_amdgcn_mfma_f32_16x16x32_bf16(Bt[n][k], At[m][k], acc[ai][bj][m][n], 0, 0, 0); __builtin_amdgcn_s_setprio(0); } while (0)
; #define PG8_WAIT_V(n) asm volatile("s_waitcnt vmcnt(" #n ")" ::: "memory")
; #define PG8_WAIT_L(n) asm volatile("s_waitcnt lgkmcnt(" #n ")" ::: "memory")
; #define PG8_BAR __builtin_amdgcn_s_barrier()
; #define PG8_SCHED __builtin_amdgcn_sched_barrier(0)
; template <class Epi, class Sched, bool ALIGN_EPI = false, bool SP2 = false>
; __device__ __forceinline__ void gemm_phase(PG8_LAS unsigned char* lds, const Gemm g, const Sched& S, const Epi& E) {
;     ...
;             PG8_LDB(B0, 0, 0); PG8_LDB(B1, 0, 1); PG8_SCHED; PG8_LDA(At, 0, 0); PG8_STAGE(PG8_SA(1, 1), a1 + hstep, voffA);
;             PG8_WAIT_V(8); PG8_WAIT_L(0); PG8_BAR; PG8_MMA(0, 0, At, B0); PG8_MMA(0, 1, At, B1); PG8_BAR; PG8_SCHED;
;             PG8_LDA(At, 0, 1); PG8_STAGE(PG8_SB(0, 0), b2, voffB); PG8_STAGE(PG8_SB(0, 1), b2 + hstep, voffB); PG8_STAGE(PG8_SA(0, 0), a2, voffA);
;             PG8_WAIT_V(8); PG8_WAIT_L(0); PG8_BAR; PG8_MMA(1, 0, At, B0); PG8_MMA(1, 1, At, B1); PG8_BAR; PG8_SCHED;
.LBB0_1167:
	s_add_u32 s26, s36, 0xfff80080
	s_addc_u32 s38, s37, -1
	s_add_i32 s63, 0, 0x10000
	s_cmp_eq_u32 s62, 28
	s_cselect_b32 s43, s17, s38
	s_cselect_b32 s42, s30, s26
	v_add_u32_e32 v144, s63, v145
	s_cselect_b32 s39, s15, s57
	s_cselect_b32 s38, s55, s56
	s_add_i32 s26, 0, 0x14000
	ds_read_b128 v[154:157], v144
	ds_read_b128 v[158:161], v144 offset:1024
	ds_read_b128 v[162:165], v144 offset:2048
	ds_read_b128 v[166:169], v144 offset:3072
	v_add_u32_e32 v144, s26, v145
	ds_read_b128 v[170:173], v144
	ds_read_b128 v[174:177], v144 offset:1024
	ds_read_b128 v[182:185], v144 offset:2048
	ds_read_b128 v[186:189], v144 offset:3072
	v_lshl_add_u64 v[146:147], s[36:37], 0, v[140:141]
	s_add_i32 m0, s45, 0xc000
	ds_read_b128 v[190:193], v153
	ds_read_b128 v[194:197], v153 offset:1024
	ds_read_b128 v[198:201], v153 offset:2048
	ds_read_b128 v[202:205], v153 offset:3072
	ds_read_b128 v[206:209], v153 offset:4096
	ds_read_b128 v[210:213], v153 offset:5120
	ds_read_b128 v[214:217], v153 offset:6144
	ds_read_b128 v[218:221], v153 offset:7168
	global_load_lds_dwordx4 v[146:147], off
	v_lshl_add_u64 v[146:147], s[36:37], 0, v[142:143]
	s_add_i32 m0, s45, 0xe000
	s_nop 0
	global_load_lds_dwordx4 v[146:147], off
	s_waitcnt vmcnt(8)
	s_waitcnt lgkmcnt(0)
	s_setprio 1
	s_barrier
	v_mfma_f32_16x16x32_bf16 v[80:83], v[154:157], v[190:193], v[80:83]
	v_mfma_f32_16x16x32_bf16 v[76:79], v[162:165], v[190:193], v[76:79]
	v_mfma_f32_16x16x32_bf16 v[64:67], v[154:157], v[198:201], v[64:67]
	v_mfma_f32_16x16x32_bf16 v[60:63], v[162:165], v[198:201], v[60:63]
	v_mfma_f32_16x16x32_bf16 v[56:59], v[154:157], v[206:209], v[56:59]
	v_mfma_f32_16x16x32_bf16 v[52:55], v[162:165], v[206:209], v[52:55]
	v_mfma_f32_16x16x32_bf16 v[44:47], v[154:157], v[214:217], v[44:47]
	v_mfma_f32_16x16x32_bf16 v[36:39], v[162:165], v[214:217], v[36:39]
	v_mfma_f32_16x16x32_bf16 v[80:83], v[158:161], v[194:197], v[80:83]
	v_mfma_f32_16x16x32_bf16 v[76:79], v[166:169], v[194:197], v[76:79]
	v_mfma_f32_16x16x32_bf16 v[64:67], v[158:161], v[202:205], v[64:67]
	v_mfma_f32_16x16x32_bf16 v[60:63], v[166:169], v[202:205], v[60:63]
	v_mfma_f32_16x16x32_bf16 v[56:59], v[158:161], v[210:213], v[56:59]
	v_mfma_f32_16x16x32_bf16 v[52:55], v[166:169], v[210:213], v[52:55]
	v_mfma_f32_16x16x32_bf16 v[44:47], v[158:161], v[218:221], v[44:47]
	v_mfma_f32_16x16x32_bf16 v[36:39], v[166:169], v[218:221], v[36:39]
	s_setprio 0
	s_setprio 1
	v_mfma_f32_16x16x32_bf16 v[128:131], v[170:173], v[190:193], v[128:131]
	v_mfma_f32_16x16x32_bf16 v[124:127], v[182:185], v[190:193], v[124:127]
	v_mfma_f32_16x16x32_bf16 v[120:123], v[170:173], v[198:201], v[120:123]
	v_mfma_f32_16x16x32_bf16 v[116:119], v[182:185], v[198:201], v[116:119]
	v_mfma_f32_16x16x32_bf16 v[112:115], v[170:173], v[206:209], v[112:115]
	v_mfma_f32_16x16x32_bf16 v[108:111], v[182:185], v[206:209], v[108:111]
	v_mfma_f32_16x16x32_bf16 v[104:107], v[170:173], v[214:217], v[104:107]
	v_mfma_f32_16x16x32_bf16 v[100:103], v[182:185], v[214:217], v[100:103]
	v_mfma_f32_16x16x32_bf16 v[128:131], v[174:177], v[194:197], v[128:131]
	v_mfma_f32_16x16x32_bf16 v[124:127], v[186:189], v[194:197], v[124:127]
	v_mfma_f32_16x16x32_bf16 v[120:123], v[174:177], v[202:205], v[120:123]
	v_mfma_f32_16x16x32_bf16 v[116:119], v[186:189], v[202:205], v[116:119]
	v_mfma_f32_16x16x32_bf16 v[112:115], v[174:177], v[210:213], v[112:115]
	v_mfma_f32_16x16x32_bf16 v[108:111], v[186:189], v[210:213], v[108:111]
	v_mfma_f32_16x16x32_bf16 v[104:107], v[174:177], v[218:221], v[104:107]
	v_mfma_f32_16x16x32_bf16 v[100:103], v[186:189], v[218:221], v[100:103]
	s_barrier
	s_setprio 0
	s_add_i32 s63, s63, s44
	v_lshl_add_u64 v[146:147], s[38:39], 0, v[2:3]
	s_mov_b32 m0, s63
	ds_read_b128 v[190:193], v153 offset:16384
	ds_read_b128 v[194:197], v153 offset:17408
	ds_read_b128 v[198:201], v153 offset:18432
	ds_read_b128 v[202:205], v153 offset:19456
	ds_read_b128 v[206:209], v153 offset:20480
	ds_read_b128 v[210:213], v153 offset:21504
	ds_read_b128 v[214:217], v153 offset:22528
	ds_read_b128 v[218:221], v153 offset:23552
	global_load_lds_dwordx4 v[146:147], off
	s_add_i32 m0, s63, 0x2000
	s_add_u32 s66, s38, 0x80000
	v_lshl_add_u64 v[150:151], s[38:39], 0, v[132:133]
	s_addc_u32 s67, s39, 0
	s_add_i32 s26, s26, s44
	global_load_lds_dwordx4 v[150:151], off
	v_lshl_add_u64 v[178:179], s[66:67], 0, v[2:3]
	s_mov_b32 m0, s26
	v_lshl_add_u64 v[222:223], s[42:43], 0, v[134:135]
	global_load_lds_dwordx4 v[178:179], off
	v_lshl_add_u64 v[178:179], s[66:67], 0, v[132:133]
	s_add_i32 m0, s26, 0x2000
	s_nop 0
	global_load_lds_dwordx4 v[178:179], off
	v_lshl_add_u64 v[178:179], s[42:43], 0, v[136:137]
	s_mov_b32 m0, s45
	s_nop 0
	global_load_lds_dwordx4 v[178:179], off
	s_mov_b32 m0, s46
	s_nop 0
	global_load_lds_dwordx4 v[222:223], off
	s_waitcnt vmcnt(8)
	s_waitcnt lgkmcnt(0)
	s_setprio 1
	s_barrier
; #define PG8_STAGE(bufoff, gbase, voff) do { _Pragma("unroll") for (int _i = 0; _i < 2; ++_i) \
;         __builtin_amdgcn_global_load_lds((const unsigned*)((const char*)(gbase) + (voff)[_i]), (PG8_LAS unsigned*)(lds + (bufoff) + ldsw + _i * 8192), 16, 0, 0); } while (0)
; #define PG8_LDA(dst, b, h) do { _Pragma("unroll") for (int m = 0; m < 4; ++m) _Pragma("unroll") for (int k = 0; k < 2; ++k) dst[m][k] = *(const PG8_LAS bf16x8*)(lds + PG8_SA(b, h) + aoff + m * 2048 + k * 1024); } while (0)
; #define PG8_LDB(dst, b, h) do { _Pragma("unroll") for (int n = 0; n < 2; ++n) _Pragma("unroll") for (int k = 0; k < 2; ++k) dst[n][k] = *(const PG8_LAS bf16x8*)(lds + PG8_SB(b, h) + boff + n * 2048 + k * 1024); } while (0)
; #define PG8_MMA(ai, bj, At, Bt) do { __builtin_amdgcn_s_setprio(1); _Pragma("unroll") for (int m = 0; m < 4; ++m) _Pragma("unroll") for (int n = 0; n < 2; ++n) _Pragma("unroll") for (int k = 0; k < 2; ++k) \
;         acc[ai][bj][m][n] = __builtin_amdgcn_mfma_f32_16x16x32_bf16(Bt[n][k], At[m][k], acc[ai][bj][m][n], 0, 0, 0); __builtin_amdgcn_s_setprio(0); } while (0)
; #define PG8_WAIT_V(n) asm volatile("s_waitcnt vmcnt(" #n ")" ::: "memory")
; #define PG8_WAIT_L(n) asm volatile("s_waitcnt lgkmcnt(" #n ")" ::: "memory")
; #define PG8_BAR __builtin_amdgcn_s_barrier()
; #define PG8_SCHED __builtin_amdgcn_sched_barrier(0)
; template <class Epi, class Sched, bool ALIGN_EPI = false, bool SP2 = false>
; __device__ __forceinline__ void gemm_phase(PG8_LAS unsigned char* lds, const Gemm g, const Sched& S, const Epi& E) {
;     ...
;             PG8_WAIT_V(8); PG8_WAIT_L(0); PG8_BAR; PG8_MMA(1, 0, At, B0); PG8_MMA(1, 1, At, B1); PG8_BAR; PG8_SCHED;
;             PG8_LDB(B0, 1, 0); PG8_LDB(B1, 1, 1); PG8_SCHED; PG8_LDA(At, 1, 0); PG8_STAGE(PG8_SA(0, 1), a2 + hstep, voffA);
;             PG8_WAIT_V(8); PG8_WAIT_L(0); PG8_BAR; PG8_MMA(0, 0, At, B0); PG8_MMA(0, 1, At, B1); PG8_BAR; PG8_SCHED;
	v_mfma_f32_16x16x32_bf16 v[32:35], v[154:157], v[190:193], v[32:35]
	v_mfma_f32_16x16x32_bf16 v[28:31], v[162:165], v[190:193], v[28:31]
	v_mfma_f32_16x16x32_bf16 v[24:27], v[154:157], v[198:201], v[24:27]
	v_mfma_f32_16x16x32_bf16 v[20:23], v[162:165], v[198:201], v[20:23]
	v_mfma_f32_16x16x32_bf16 v[16:19], v[154:157], v[206:209], v[16:19]
	v_mfma_f32_16x16x32_bf16 v[12:15], v[162:165], v[206:209], v[12:15]
	v_mfma_f32_16x16x32_bf16 v[8:11], v[154:157], v[214:217], v[8:11]
	v_mfma_f32_16x16x32_bf16 v[4:7], v[162:165], v[214:217], v[4:7]
	v_mfma_f32_16x16x32_bf16 v[32:35], v[158:161], v[194:197], v[32:35]
	v_mfma_f32_16x16x32_bf16 v[28:31], v[166:169], v[194:197], v[28:31]
	v_mfma_f32_16x16x32_bf16 v[24:27], v[158:161], v[202:205], v[24:27]
	v_mfma_f32_16x16x32_bf16 v[20:23], v[166:169], v[202:205], v[20:23]
	v_mfma_f32_16x16x32_bf16 v[16:19], v[158:161], v[210:213], v[16:19]
	v_mfma_f32_16x16x32_bf16 v[12:15], v[166:169], v[210:213], v[12:15]
	v_mfma_f32_16x16x32_bf16 v[8:11], v[158:161], v[218:221], v[8:11]
	v_mfma_f32_16x16x32_bf16 v[4:7], v[166:169], v[218:221], v[4:7]
	s_setprio 0
	s_setprio 1
	v_mfma_f32_16x16x32_bf16 v[96:99], v[170:173], v[190:193], v[96:99]
	v_mfma_f32_16x16x32_bf16 v[92:95], v[182:185], v[190:193], v[92:95]
	v_mfma_f32_16x16x32_bf16 v[88:91], v[170:173], v[198:201], v[88:91]
	v_mfma_f32_16x16x32_bf16 v[84:87], v[182:185], v[198:201], v[84:87]
	v_mfma_f32_16x16x32_bf16 v[72:75], v[170:173], v[206:209], v[72:75]
	v_mfma_f32_16x16x32_bf16 v[68:71], v[182:185], v[206:209], v[68:71]
	v_mfma_f32_16x16x32_bf16 v[48:51], v[170:173], v[214:217], v[48:51]
	v_mfma_f32_16x16x32_bf16 v[40:43], v[182:185], v[214:217], v[40:43]
	v_mfma_f32_16x16x32_bf16 v[96:99], v[174:177], v[194:197], v[96:99]
	v_mfma_f32_16x16x32_bf16 v[92:95], v[186:189], v[194:197], v[92:95]
	v_mfma_f32_16x16x32_bf16 v[88:91], v[174:177], v[202:205], v[88:91]
	v_mfma_f32_16x16x32_bf16 v[84:87], v[186:189], v[202:205], v[84:87]
	v_mfma_f32_16x16x32_bf16 v[72:75], v[174:177], v[210:213], v[72:75]
	v_mfma_f32_16x16x32_bf16 v[68:71], v[186:189], v[210:213], v[68:71]
	v_mfma_f32_16x16x32_bf16 v[48:51], v[174:177], v[218:221], v[48:51]
	v_mfma_f32_16x16x32_bf16 v[40:43], v[186:189], v[218:221], v[40:43]
	s_barrier
	s_setprio 0
	s_add_i32 s26, 0, 0x18000
	v_add_u32_e32 v144, s26, v145
	s_add_i32 s63, 0, 0x1c000
	ds_read_b128 v[154:157], v144
	ds_read_b128 v[158:161], v144 offset:1024
	ds_read_b128 v[162:165], v144 offset:2048
	ds_read_b128 v[166:169], v144 offset:3072
	v_add_u32_e32 v144, s63, v145
	ds_read_b128 v[170:173], v144
	ds_read_b128 v[174:177], v144 offset:1024
	ds_read_b128 v[182:185], v144 offset:2048
	ds_read_b128 v[186:189], v144 offset:3072
	s_add_u32 s42, s42, 0x80000
	s_addc_u32 s43, s43, 0
	s_mov_b32 m0, s47
	v_lshl_add_u64 v[224:225], s[42:43], 0, v[136:137]
	ds_read_b128 v[190:193], v153 offset:32768
	ds_read_b128 v[194:197], v153 offset:33792
	ds_read_b128 v[198:201], v153 offset:34816
	ds_read_b128 v[202:205], v153 offset:35840
	ds_read_b128 v[206:209], v153 offset:36864
	ds_read_b128 v[210:213], v153 offset:37888
	ds_read_b128 v[214:217], v153 offset:38912
	ds_read_b128 v[218:221], v153 offset:39936
	global_load_lds_dwordx4 v[224:225], off
	v_lshl_add_u64 v[224:225], s[42:43], 0, v[134:135]
	s_mov_b32 m0, s50
	s_nop 0
	global_load_lds_dwordx4 v[224:225], off
	s_waitcnt vmcnt(8)
	s_waitcnt lgkmcnt(0)
	s_setprio 1
	s_barrier
	v_mfma_f32_16x16x32_bf16 v[80:83], v[154:157], v[190:193], v[80:83]
	v_mfma_f32_16x16x32_bf16 v[76:79], v[162:165], v[190:193], v[76:79]
	v_mfma_f32_16x16x32_bf16 v[64:67], v[154:157], v[198:201], v[64:67]
	v_mfma_f32_16x16x32_bf16 v[60:63], v[162:165], v[198:201], v[60:63]
	v_mfma_f32_16x16x32_bf16 v[56:59], v[154:157], v[206:209], v[56:59]
	v_mfma_f32_16x16x32_bf16 v[52:55], v[162:165], v[206:209], v[52:55]
	v_mfma_f32_16x16x32_bf16 v[44:47], v[154:157], v[214:217], v[44:47]
	v_mfma_f32_16x16x32_bf16 v[36:39], v[162:165], v[214:217], v[36:39]
	v_mfma_f32_16x16x32_bf16 v[80:83], v[158:161], v[194:197], v[80:83]
	v_mfma_f32_16x16x32_bf16 v[76:79], v[166:169], v[194:197], v[76:79]
	v_mfma_f32_16x16x32_bf16 v[64:67], v[158:161], v[202:205], v[64:67]
	v_mfma_f32_16x16x32_bf16 v[60:63], v[166:169], v[202:205], v[60:63]
	v_mfma_f32_16x16x32_bf16 v[56:59], v[158:161], v[210:213], v[56:59]
	v_mfma_f32_16x16x32_bf16 v[52:55], v[166:169], v[210:213], v[52:55]
	v_mfma_f32_16x16x32_bf16 v[44:47], v[158:161], v[218:221], v[44:47]
	v_mfma_f32_16x16x32_bf16 v[36:39], v[166:169], v[218:221], v[36:39]
	s_setprio 0
	s_setprio 1
	v_mfma_f32_16x16x32_bf16 v[128:131], v[170:173], v[190:193], v[128:131]
	v_mfma_f32_16x16x32_bf16 v[124:127], v[182:185], v[190:193], v[124:127]
	v_mfma_f32_16x16x32_bf16 v[120:123], v[170:173], v[198:201], v[120:123]
	v_mfma_f32_16x16x32_bf16 v[116:119], v[182:185], v[198:201], v[116:119]
	v_mfma_f32_16x16x32_bf16 v[112:115], v[170:173], v[206:209], v[112:115]
	v_mfma_f32_16x16x32_bf16 v[108:111], v[182:185], v[206:209], v[108:111]
	v_mfma_f32_16x16x32_bf16 v[104:107], v[170:173], v[214:217], v[104:107]
	v_mfma_f32_16x16x32_bf16 v[100:103], v[182:185], v[214:217], v[100:103]
	v_mfma_f32_16x16x32_bf16 v[128:131], v[174:177], v[194:197], v[128:131]
	v_mfma_f32_16x16x32_bf16 v[124:127], v[186:189], v[194:197], v[124:127]
	v_mfma_f32_16x16x32_bf16 v[120:123], v[174:177], v[202:205], v[120:123]
	v_mfma_f32_16x16x32_bf16 v[116:119], v[186:189], v[202:205], v[116:119]
	v_mfma_f32_16x16x32_bf16 v[112:115], v[174:177], v[210:213], v[112:115]
	v_mfma_f32_16x16x32_bf16 v[108:111], v[186:189], v[210:213], v[108:111]
	v_mfma_f32_16x16x32_bf16 v[104:107], v[174:177], v[218:221], v[104:107]
	v_mfma_f32_16x16x32_bf16 v[100:103], v[186:189], v[218:221], v[100:103]
	s_barrier
; #define PG8_STAGE(bufoff, gbase, voff) do { _Pragma("unroll") for (int _i = 0; _i < 2; ++_i) \
;         __builtin_amdgcn_global_load_lds((const unsigned*)((const char*)(gbase) + (voff)[_i]), (PG8_LAS unsigned*)(lds + (bufoff) + ldsw + _i * 8192), 16, 0, 0); } while (0)
; #define PG8_LDA(dst, b, h) do { _Pragma("unroll") for (int m = 0; m < 4; ++m) _Pragma("unroll") for (int k = 0; k < 2; ++k) dst[m][k] = *(const PG8_LAS bf16x8*)(lds + PG8_SA(b, h) + aoff + m * 2048 + k * 1024); } while (0)
; #define PG8_MMA(ai, bj, At, Bt) do { __builtin_amdgcn_s_setprio(1); _Pragma("unroll") for (int m = 0; m < 4; ++m) _Pragma("unroll") for (int n = 0; n < 2; ++n) _Pragma("unroll") for (int k = 0; k < 2; ++k) \
;         acc[ai][bj][m][n] = __builtin_amdgcn_mfma_f32_16x16x32_bf16(Bt[n][k], At[m][k], acc[ai][bj][m][n], 0, 0, 0); __builtin_amdgcn_s_setprio(0); } while (0)
; #define PG8_WAIT_V(n) asm volatile("s_waitcnt vmcnt(" #n ")" ::: "memory")
; #define PG8_WAIT_L(n) asm volatile("s_waitcnt lgkmcnt(" #n ")" ::: "memory")
; #define PG8_BAR __builtin_amdgcn_s_barrier()
; #define PG8_SCHED __builtin_amdgcn_sched_barrier(0)
; template <class Epi, class Sched, bool ALIGN_EPI = false, bool SP2 = false>
; __device__ __forceinline__ void gemm_phase(PG8_LAS unsigned char* lds, const Gemm g, const Sched& S, const Epi& E) {
;     ...
;         for (int t = 0; t < nt; t += 2) {
;             const bool last = (t == nt - 2);
;             const char* a1 = cA + (size_t)(t + 1) * kstep;
;             const char* a2 = last ? nA : cA + (size_t)(t + 2) * kstep; const char* b2 = last ? nB : cB + (size_t)(t + 2) * kstep;
;     ...
;             PG8_LDA(At, 1, 1); PG8_STAGE(PG8_SB(1, 0), b3, voffB); PG8_STAGE(PG8_SB(1, 1), b3 + hstep, voffB); PG8_STAGE(PG8_SA(1, 0), a3, voffA);
;             PG8_WAIT_V(8); PG8_WAIT_L(0); PG8_BAR; PG8_MMA(1, 0, At, B0); PG8_MMA(1, 1, At, B1); PG8_BAR; PG8_SCHED;
	s_setprio 0
	s_add_i32 s26, s26, s44
	v_lshl_add_u64 v[146:147], v[146:147], 0, s[60:61]
	s_mov_b32 m0, s26
	ds_read_b128 v[190:193], v153 offset:49152
	ds_read_b128 v[194:197], v153 offset:50176
	ds_read_b128 v[198:201], v153 offset:51200
	ds_read_b128 v[202:205], v153 offset:52224
	ds_read_b128 v[206:209], v153 offset:53248
	ds_read_b128 v[210:213], v153 offset:54272
	ds_read_b128 v[214:217], v153 offset:55296
	ds_read_b128 v[218:221], v153 offset:56320
	global_load_lds_dwordx4 v[146:147], off
	s_add_i32 m0, s26, 0x2000
	s_add_u32 s38, s38, 0x80080
	v_lshl_add_u64 v[146:147], v[150:151], 0, s[60:61]
	s_addc_u32 s39, s39, 0
	s_add_i32 s26, s63, s44
	global_load_lds_dwordx4 v[146:147], off
	v_lshl_add_u64 v[146:147], s[38:39], 0, v[2:3]
	s_mov_b32 m0, s26
	s_nop 0
	global_load_lds_dwordx4 v[146:147], off
	v_lshl_add_u64 v[146:147], s[38:39], 0, v[132:133]
	s_add_i32 m0, s26, 0x2000
	s_nop 0
	global_load_lds_dwordx4 v[146:147], off
	v_lshl_add_u64 v[146:147], v[178:179], 0, s[60:61]
	s_mov_b32 m0, s51
	s_nop 0
	global_load_lds_dwordx4 v[146:147], off
	v_lshl_add_u64 v[146:147], v[222:223], 0, s[60:61]
	s_mov_b32 m0, s52
	s_nop 0
	global_load_lds_dwordx4 v[146:147], off
	s_waitcnt vmcnt(8)
	s_waitcnt lgkmcnt(0)
	s_setprio 1
	s_barrier
	v_mfma_f32_16x16x32_bf16 v[32:35], v[154:157], v[190:193], v[32:35]
	v_mfma_f32_16x16x32_bf16 v[28:31], v[162:165], v[190:193], v[28:31]
	v_mfma_f32_16x16x32_bf16 v[24:27], v[154:157], v[198:201], v[24:27]
	v_mfma_f32_16x16x32_bf16 v[20:23], v[162:165], v[198:201], v[20:23]
	v_mfma_f32_16x16x32_bf16 v[16:19], v[154:157], v[206:209], v[16:19]
	v_mfma_f32_16x16x32_bf16 v[12:15], v[162:165], v[206:209], v[12:15]
	v_mfma_f32_16x16x32_bf16 v[8:11], v[154:157], v[214:217], v[8:11]
	v_mfma_f32_16x16x32_bf16 v[4:7], v[162:165], v[214:217], v[4:7]
	v_mfma_f32_16x16x32_bf16 v[32:35], v[158:161], v[194:197], v[32:35]
	v_mfma_f32_16x16x32_bf16 v[28:31], v[166:169], v[194:197], v[28:31]
	v_mfma_f32_16x16x32_bf16 v[24:27], v[158:161], v[202:205], v[24:27]
	v_mfma_f32_16x16x32_bf16 v[20:23], v[166:169], v[202:205], v[20:23]
	v_mfma_f32_16x16x32_bf16 v[16:19], v[158:161], v[210:213], v[16:19]
	v_mfma_f32_16x16x32_bf16 v[12:15], v[166:169], v[210:213], v[12:15]
	v_mfma_f32_16x16x32_bf16 v[8:11], v[158:161], v[218:221], v[8:11]
	v_mfma_f32_16x16x32_bf16 v[4:7], v[166:169], v[218:221], v[4:7]
	s_setprio 0
	s_setprio 1
	v_mfma_f32_16x16x32_bf16 v[96:99], v[170:173], v[190:193], v[96:99]
	v_mfma_f32_16x16x32_bf16 v[92:95], v[182:185], v[190:193], v[92:95]
	v_mfma_f32_16x16x32_bf16 v[88:91], v[170:173], v[198:201], v[88:91]
	v_mfma_f32_16x16x32_bf16 v[84:87], v[182:185], v[198:201], v[84:87]
	v_mfma_f32_16x16x32_bf16 v[72:75], v[170:173], v[206:209], v[72:75]
	v_mfma_f32_16x16x32_bf16 v[68:71], v[182:185], v[206:209], v[68:71]
	v_mfma_f32_16x16x32_bf16 v[48:51], v[170:173], v[214:217], v[48:51]
	v_mfma_f32_16x16x32_bf16 v[40:43], v[182:185], v[214:217], v[40:43]
	v_mfma_f32_16x16x32_bf16 v[96:99], v[174:177], v[194:197], v[96:99]
	v_mfma_f32_16x16x32_bf16 v[92:95], v[186:189], v[194:197], v[92:95]
	v_mfma_f32_16x16x32_bf16 v[88:91], v[174:177], v[202:205], v[88:91]
	v_mfma_f32_16x16x32_bf16 v[84:87], v[186:189], v[202:205], v[84:87]
	v_mfma_f32_16x16x32_bf16 v[72:75], v[174:177], v[210:213], v[72:75]
	v_mfma_f32_16x16x32_bf16 v[68:71], v[186:189], v[210:213], v[68:71]
	v_mfma_f32_16x16x32_bf16 v[48:51], v[174:177], v[218:221], v[48:51]
	v_mfma_f32_16x16x32_bf16 v[40:43], v[186:189], v[218:221], v[40:43]
	s_barrier
	s_setprio 0
	s_add_i32 s62, s62, 2
	s_add_u32 s36, s36, 0x100
	s_addc_u32 s37, s37, 0
	s_add_u32 s56, s56, 0x100
	s_addc_u32 s57, s57, 0
	s_cmp_gt_u32 s62, 29
	s_cbranch_scc0 .LBB0_1167
	s_and_b64 vcc, exec, s[10:11]
	s_cbranch_vccz .LBB0_1170
	s_barrier

; #define PG8_STAGE(bufoff, gbase, voff) do { _Pragma("unroll") for (int _i = 0; _i < 2; ++_i) \
;         __builtin_amdgcn_global_load_lds((const unsigned*)((const char*)(gbase) + (voff)[_i]), (PG8_LAS unsigned*)(lds + (bufoff) + ldsw + _i * 8192), 16, 0, 0); } while (0)
; #define PG8_LDA(dst, b, h) do { _Pragma("unroll") for (int m = 0; m < 4; ++m) _Pragma("unroll") for (int k = 0; k < 2; ++k) dst[m][k] = *(const PG8_LAS bf16x8*)(lds + PG8_SA(b, h) + aoff + m * 2048 + k * 1024); } while (0)
; #define PG8_LDB(dst, b, h) do { _Pragma("unroll") for (int n = 0; n < 2; ++n) _Pragma("unroll") for (int k = 0; k < 2; ++k) dst[n][k] = *(const PG8_LAS bf16x8*)(lds + PG8_SB(b, h) + boff + n * 2048 + k * 1024); } while (0)
; #define PG8_MMA(ai, bj, At, Bt) do { __builtin_amdgcn_s_setprio(1); _Pragma("unroll") for (int m = 0; m < 4; ++m) _Pragma("unroll") for (int n = 0; n < 2; ++n) _Pragma("unroll") for (int k = 0; k < 2; ++k) \
;         acc[ai][bj][m][n] = __builtin_amdgcn_mfma_f32_16x16x32_bf16(Bt[n][k], At[m][k], acc[ai][bj][m][n], 0, 0, 0); __builtin_amdgcn_s_setprio(0); } while (0)
; #define PG8_WAIT_V(n) asm volatile("s_waitcnt vmcnt(" #n ")" ::: "memory")
; #define PG8_WAIT_L(n) asm volatile("s_waitcnt lgkmcnt(" #n ")" ::: "memory")
; #define PG8_BAR __builtin_amdgcn_s_barrier()
; #define PG8_SCHED __builtin_amdgcn_sched_barrier(0)
; template <class Epi, class Sched, bool ALIGN_EPI = false, bool SP2 = false>
; __device__ __forceinline__ void gemm_phase(PG8_LAS unsigned char* lds, const Gemm g, const Sched& S, const Epi& E) {
;     ...
;             PG8_LDB(B0, 0, 0); PG8_LDB(B1, 0, 1); PG8_SCHED; PG8_LDA(At, 0, 0); PG8_STAGE(PG8_SA(1, 1), a1 + hstep, voffA);
;             PG8_WAIT_V(8); PG8_WAIT_L(0); PG8_BAR; PG8_MMA(0, 0, At, B0); PG8_MMA(0, 1, At, B1); PG8_BAR; PG8_SCHED;
;             PG8_LDA(At, 0, 1); PG8_STAGE(PG8_SB(0, 0), b2, voffB); PG8_STAGE(PG8_SB(0, 1), b2 + hstep, voffB); PG8_STAGE(PG8_SA(0, 0), a2, voffA);
;             PG8_WAIT_V(8); PG8_WAIT_L(0); PG8_BAR; PG8_MMA(1, 0, At, B0); PG8_MMA(1, 1, At, B1); PG8_BAR; PG8_SCHED;
.LBB0_1961:
	s_add_u32 s26, s38, 0xfff80080
	s_addc_u32 s31, s39, -1
	s_add_i32 s67, 0, 0x10000
	s_cmp_eq_u32 s66, 28
	s_cselect_b32 s45, s21, s31
	s_cselect_b32 s44, s57, s26
	s_cselect_b32 s43, s19, s64
	s_cselect_b32 s42, s62, s63
	s_add_i32 s26, 0, 0x14000
	v_add_u32_e32 v128, s67, v178
	v_add_u32_e32 v170, s26, v178
	ds_read_b128 v[116:119], v128
	ds_read_b128 v[120:123], v128 offset:1024
	ds_read_b128 v[124:127], v128 offset:2048
	ds_read_b128 v[128:131], v128 offset:3072
	ds_read_b128 v[132:135], v170
	ds_read_b128 v[136:139], v170 offset:1024
	ds_read_b128 v[166:169], v170 offset:2048
	ds_read_b128 v[170:173], v170 offset:3072
	v_lshl_add_u64 v[210:211], s[38:39], 0, v[162:163]
	s_add_i32 m0, s47, 0xc000
	ds_read_b128 v[174:177], v181
	ds_read_b128 v[182:185], v181 offset:1024
	ds_read_b128 v[186:189], v181 offset:2048
	ds_read_b128 v[190:193], v181 offset:3072
	ds_read_b128 v[194:197], v181 offset:4096
	ds_read_b128 v[198:201], v181 offset:5120
	ds_read_b128 v[202:205], v181 offset:6144
	ds_read_b128 v[206:209], v181 offset:7168
	global_load_lds_dwordx4 v[210:211], off
	v_lshl_add_u64 v[210:211], s[38:39], 0, v[164:165]
	s_add_i32 m0, s47, 0xe000
	s_nop 0
	global_load_lds_dwordx4 v[210:211], off
	s_waitcnt vmcnt(8)
	s_waitcnt lgkmcnt(0)
	s_setprio 1
	s_barrier
	v_mfma_f32_16x16x32_bf16 v[152:155], v[116:119], v[174:177], v[152:155]
	v_mfma_f32_16x16x32_bf16 v[148:151], v[124:127], v[174:177], v[148:151]
	v_mfma_f32_16x16x32_bf16 v[112:115], v[116:119], v[186:189], v[112:115]
	v_mfma_f32_16x16x32_bf16 v[108:111], v[124:127], v[186:189], v[108:111]
	v_mfma_f32_16x16x32_bf16 v[96:99], v[116:119], v[194:197], v[96:99]
	v_mfma_f32_16x16x32_bf16 v[92:95], v[124:127], v[194:197], v[92:95]
	v_mfma_f32_16x16x32_bf16 v[80:83], v[116:119], v[202:205], v[80:83]
	v_mfma_f32_16x16x32_bf16 v[76:79], v[124:127], v[202:205], v[76:79]
	v_mfma_f32_16x16x32_bf16 v[152:155], v[120:123], v[182:185], v[152:155]
	v_mfma_f32_16x16x32_bf16 v[148:151], v[128:131], v[182:185], v[148:151]
	v_mfma_f32_16x16x32_bf16 v[112:115], v[120:123], v[190:193], v[112:115]
	v_mfma_f32_16x16x32_bf16 v[108:111], v[128:131], v[190:193], v[108:111]
	v_mfma_f32_16x16x32_bf16 v[96:99], v[120:123], v[198:201], v[96:99]
	v_mfma_f32_16x16x32_bf16 v[92:95], v[128:131], v[198:201], v[92:95]
	v_mfma_f32_16x16x32_bf16 v[80:83], v[120:123], v[206:209], v[80:83]
	v_mfma_f32_16x16x32_bf16 v[76:79], v[128:131], v[206:209], v[76:79]
	s_setprio 0
	s_setprio 1
	v_mfma_f32_16x16x32_bf16 v[144:147], v[132:135], v[174:177], v[144:147]
	v_mfma_f32_16x16x32_bf16 v[140:143], v[166:169], v[174:177], v[140:143]
	v_mfma_f32_16x16x32_bf16 v[104:107], v[132:135], v[186:189], v[104:107]
	v_mfma_f32_16x16x32_bf16 v[100:103], v[166:169], v[186:189], v[100:103]
	v_mfma_f32_16x16x32_bf16 v[88:91], v[132:135], v[194:197], v[88:91]
	v_mfma_f32_16x16x32_bf16 v[84:87], v[166:169], v[194:197], v[84:87]
	v_mfma_f32_16x16x32_bf16 v[72:75], v[132:135], v[202:205], v[72:75]
	v_mfma_f32_16x16x32_bf16 v[68:71], v[166:169], v[202:205], v[68:71]
	v_mfma_f32_16x16x32_bf16 v[144:147], v[136:139], v[182:185], v[144:147]
	v_mfma_f32_16x16x32_bf16 v[140:143], v[170:173], v[182:185], v[140:143]
	v_mfma_f32_16x16x32_bf16 v[104:107], v[136:139], v[190:193], v[104:107]
	v_mfma_f32_16x16x32_bf16 v[100:103], v[170:173], v[190:193], v[100:103]
	v_mfma_f32_16x16x32_bf16 v[88:91], v[136:139], v[198:201], v[88:91]
	v_mfma_f32_16x16x32_bf16 v[84:87], v[170:173], v[198:201], v[84:87]
	v_mfma_f32_16x16x32_bf16 v[72:75], v[136:139], v[206:209], v[72:75]
	v_mfma_f32_16x16x32_bf16 v[68:71], v[170:173], v[206:209], v[68:71]
	s_barrier
	s_setprio 0
	s_add_i32 s31, s67, s46
	v_lshl_add_u64 v[210:211], s[42:43], 0, v[2:3]
	s_mov_b32 m0, s31
	ds_read_b128 v[174:177], v181 offset:16384
	ds_read_b128 v[182:185], v181 offset:17408
	ds_read_b128 v[186:189], v181 offset:18432
	ds_read_b128 v[190:193], v181 offset:19456
	ds_read_b128 v[194:197], v181 offset:20480
	ds_read_b128 v[198:201], v181 offset:21504
	ds_read_b128 v[202:205], v181 offset:22528
	ds_read_b128 v[206:209], v181 offset:23552
	global_load_lds_dwordx4 v[210:211], off
	s_add_i32 m0, s31, 0x2000
	s_add_u32 s68, s42, 0x80000
	v_lshl_add_u64 v[212:213], s[42:43], 0, v[156:157]
	s_addc_u32 s69, s43, 0
	s_add_i32 s26, s26, s46
	global_load_lds_dwordx4 v[212:213], off
	v_lshl_add_u64 v[214:215], s[68:69], 0, v[2:3]
	s_mov_b32 m0, s26
	v_lshl_add_u64 v[216:217], s[44:45], 0, v[158:159]
	global_load_lds_dwordx4 v[214:215], off
	v_lshl_add_u64 v[214:215], s[68:69], 0, v[156:157]
	s_add_i32 m0, s26, 0x2000
	s_nop 0
	global_load_lds_dwordx4 v[214:215], off
	v_lshl_add_u64 v[214:215], s[44:45], 0, v[160:161]
	s_mov_b32 m0, s47
	s_nop 0
	global_load_lds_dwordx4 v[214:215], off
	s_mov_b32 m0, s50
	s_nop 0
	global_load_lds_dwordx4 v[216:217], off
	s_waitcnt vmcnt(8)
	s_waitcnt lgkmcnt(0)
	s_setprio 1
	s_barrier
; #define PG8_STAGE(bufoff, gbase, voff) do { _Pragma("unroll") for (int _i = 0; _i < 2; ++_i) \
;         __builtin_amdgcn_global_load_lds((const unsigned*)((const char*)(gbase) + (voff)[_i]), (PG8_LAS unsigned*)(lds + (bufoff) + ldsw + _i * 8192), 16, 0, 0); } while (0)
; #define PG8_LDA(dst, b, h) do { _Pragma("unroll") for (int m = 0; m < 4; ++m) _Pragma("unroll") for (int k = 0; k < 2; ++k) dst[m][k] = *(const PG8_LAS bf16x8*)(lds + PG8_SA(b, h) + aoff + m * 2048 + k * 1024); } while (0)
; #define PG8_LDB(dst, b, h) do { _Pragma("unroll") for (int n = 0; n < 2; ++n) _Pragma("unroll") for (int k = 0; k < 2; ++k) dst[n][k] = *(const PG8_LAS bf16x8*)(lds + PG8_SB(b, h) + boff + n * 2048 + k * 1024); } while (0)
; #define PG8_MMA(ai, bj, At, Bt) do { __builtin_amdgcn_s_setprio(1); _Pragma("unroll") for (int m = 0; m < 4; ++m) _Pragma("unroll") for (int n = 0; n < 2; ++n) _Pragma("unroll") for (int k = 0; k < 2; ++k) \
;         acc[ai][bj][m][n] = __builtin_amdgcn_mfma_f32_16x16x32_bf16(Bt[n][k], At[m][k], acc[ai][bj][m][n], 0, 0, 0); __builtin_amdgcn_s_setprio(0); } while (0)
; #define PG8_WAIT_V(n) asm volatile("s_waitcnt vmcnt(" #n ")" ::: "memory")
; #define PG8_WAIT_L(n) asm volatile("s_waitcnt lgkmcnt(" #n ")" ::: "memory")
; #define PG8_BAR __builtin_amdgcn_s_barrier()
; #define PG8_SCHED __builtin_amdgcn_sched_barrier(0)
; template <class Epi, class Sched, bool ALIGN_EPI = false, bool SP2 = false>
; __device__ __forceinline__ void gemm_phase(PG8_LAS unsigned char* lds, const Gemm g, const Sched& S, const Epi& E) {
;     ...
;             PG8_WAIT_V(8); PG8_WAIT_L(0); PG8_BAR; PG8_MMA(1, 0, At, B0); PG8_MMA(1, 1, At, B1); PG8_BAR; PG8_SCHED;
;             PG8_LDB(B0, 1, 0); PG8_LDB(B1, 1, 1); PG8_SCHED; PG8_LDA(At, 1, 0); PG8_STAGE(PG8_SA(0, 1), a2 + hstep, voffA);
;             PG8_WAIT_V(8); PG8_WAIT_L(0); PG8_BAR; PG8_MMA(0, 0, At, B0); PG8_MMA(0, 1, At, B1); PG8_BAR; PG8_SCHED;
	v_mfma_f32_16x16x32_bf16 v[64:67], v[116:119], v[174:177], v[64:67]
	v_mfma_f32_16x16x32_bf16 v[60:63], v[124:127], v[174:177], v[60:63]
	v_mfma_f32_16x16x32_bf16 v[48:51], v[116:119], v[186:189], v[48:51]
	v_mfma_f32_16x16x32_bf16 v[44:47], v[124:127], v[186:189], v[44:47]
	v_mfma_f32_16x16x32_bf16 v[32:35], v[116:119], v[194:197], v[32:35]
	v_mfma_f32_16x16x32_bf16 v[28:31], v[124:127], v[194:197], v[28:31]
	v_mfma_f32_16x16x32_bf16 v[16:19], v[116:119], v[202:205], v[16:19]
	v_mfma_f32_16x16x32_bf16 v[12:15], v[124:127], v[202:205], v[12:15]
	v_mfma_f32_16x16x32_bf16 v[64:67], v[120:123], v[182:185], v[64:67]
	v_mfma_f32_16x16x32_bf16 v[60:63], v[128:131], v[182:185], v[60:63]
	v_mfma_f32_16x16x32_bf16 v[48:51], v[120:123], v[190:193], v[48:51]
	v_mfma_f32_16x16x32_bf16 v[44:47], v[128:131], v[190:193], v[44:47]
	v_mfma_f32_16x16x32_bf16 v[32:35], v[120:123], v[198:201], v[32:35]
	v_mfma_f32_16x16x32_bf16 v[28:31], v[128:131], v[198:201], v[28:31]
	v_mfma_f32_16x16x32_bf16 v[16:19], v[120:123], v[206:209], v[16:19]
	v_mfma_f32_16x16x32_bf16 v[12:15], v[128:131], v[206:209], v[12:15]
	s_setprio 0
	s_setprio 1
	v_mfma_f32_16x16x32_bf16 v[56:59], v[132:135], v[174:177], v[56:59]
	v_mfma_f32_16x16x32_bf16 v[52:55], v[166:169], v[174:177], v[52:55]
	v_mfma_f32_16x16x32_bf16 v[40:43], v[132:135], v[186:189], v[40:43]
	v_mfma_f32_16x16x32_bf16 v[36:39], v[166:169], v[186:189], v[36:39]
	v_mfma_f32_16x16x32_bf16 v[24:27], v[132:135], v[194:197], v[24:27]
	v_mfma_f32_16x16x32_bf16 v[20:23], v[166:169], v[194:197], v[20:23]
	v_mfma_f32_16x16x32_bf16 v[8:11], v[132:135], v[202:205], v[8:11]
	v_mfma_f32_16x16x32_bf16 v[4:7], v[166:169], v[202:205], v[4:7]
	v_mfma_f32_16x16x32_bf16 v[56:59], v[136:139], v[182:185], v[56:59]
	v_mfma_f32_16x16x32_bf16 v[52:55], v[170:173], v[182:185], v[52:55]
	v_mfma_f32_16x16x32_bf16 v[40:43], v[136:139], v[190:193], v[40:43]
	v_mfma_f32_16x16x32_bf16 v[36:39], v[170:173], v[190:193], v[36:39]
	v_mfma_f32_16x16x32_bf16 v[24:27], v[136:139], v[198:201], v[24:27]
	v_mfma_f32_16x16x32_bf16 v[20:23], v[170:173], v[198:201], v[20:23]
	v_mfma_f32_16x16x32_bf16 v[8:11], v[136:139], v[206:209], v[8:11]
	v_mfma_f32_16x16x32_bf16 v[4:7], v[170:173], v[206:209], v[4:7]
	s_barrier
	s_setprio 0
	s_add_i32 s26, 0, 0x18000
	s_add_i32 s31, 0, 0x1c000
	v_add_u32_e32 v128, s26, v178
	v_add_u32_e32 v170, s31, v178
	ds_read_b128 v[116:119], v128
	ds_read_b128 v[120:123], v128 offset:1024
	ds_read_b128 v[124:127], v128 offset:2048
	ds_read_b128 v[128:131], v128 offset:3072
	ds_read_b128 v[132:135], v170
	ds_read_b128 v[136:139], v170 offset:1024
	ds_read_b128 v[166:169], v170 offset:2048
	ds_read_b128 v[170:173], v170 offset:3072
	s_add_u32 s44, s44, 0x80000
	s_addc_u32 s45, s45, 0
	s_mov_b32 m0, s51
	v_lshl_add_u64 v[218:219], s[44:45], 0, v[160:161]
	ds_read_b128 v[174:177], v181 offset:32768
	ds_read_b128 v[182:185], v181 offset:33792
	ds_read_b128 v[186:189], v181 offset:34816
	ds_read_b128 v[190:193], v181 offset:35840
	ds_read_b128 v[194:197], v181 offset:36864
	ds_read_b128 v[198:201], v181 offset:37888
	ds_read_b128 v[202:205], v181 offset:38912
	ds_read_b128 v[206:209], v181 offset:39936
	global_load_lds_dwordx4 v[218:219], off
	v_lshl_add_u64 v[218:219], s[44:45], 0, v[158:159]
	s_mov_b32 m0, s52
	s_nop 0
	global_load_lds_dwordx4 v[218:219], off
	s_waitcnt vmcnt(8)
	s_waitcnt lgkmcnt(0)
	s_setprio 1
	s_barrier
	v_mfma_f32_16x16x32_bf16 v[152:155], v[116:119], v[174:177], v[152:155]
	v_mfma_f32_16x16x32_bf16 v[148:151], v[124:127], v[174:177], v[148:151]
	v_mfma_f32_16x16x32_bf16 v[112:115], v[116:119], v[186:189], v[112:115]
	v_mfma_f32_16x16x32_bf16 v[108:111], v[124:127], v[186:189], v[108:111]
	v_mfma_f32_16x16x32_bf16 v[96:99], v[116:119], v[194:197], v[96:99]
	v_mfma_f32_16x16x32_bf16 v[92:95], v[124:127], v[194:197], v[92:95]
	v_mfma_f32_16x16x32_bf16 v[80:83], v[116:119], v[202:205], v[80:83]
	v_mfma_f32_16x16x32_bf16 v[76:79], v[124:127], v[202:205], v[76:79]
	v_mfma_f32_16x16x32_bf16 v[152:155], v[120:123], v[182:185], v[152:155]
	v_mfma_f32_16x16x32_bf16 v[148:151], v[128:131], v[182:185], v[148:151]
	v_mfma_f32_16x16x32_bf16 v[112:115], v[120:123], v[190:193], v[112:115]
	v_mfma_f32_16x16x32_bf16 v[108:111], v[128:131], v[190:193], v[108:111]
	v_mfma_f32_16x16x32_bf16 v[96:99], v[120:123], v[198:201], v[96:99]
	v_mfma_f32_16x16x32_bf16 v[92:95], v[128:131], v[198:201], v[92:95]
	v_mfma_f32_16x16x32_bf16 v[80:83], v[120:123], v[206:209], v[80:83]
	v_mfma_f32_16x16x32_bf16 v[76:79], v[128:131], v[206:209], v[76:79]
	s_setprio 0
	s_setprio 1
	v_mfma_f32_16x16x32_bf16 v[144:147], v[132:135], v[174:177], v[144:147]
	v_mfma_f32_16x16x32_bf16 v[140:143], v[166:169], v[174:177], v[140:143]
	v_mfma_f32_16x16x32_bf16 v[104:107], v[132:135], v[186:189], v[104:107]
	v_mfma_f32_16x16x32_bf16 v[100:103], v[166:169], v[186:189], v[100:103]
	v_mfma_f32_16x16x32_bf16 v[88:91], v[132:135], v[194:197], v[88:91]
	v_mfma_f32_16x16x32_bf16 v[84:87], v[166:169], v[194:197], v[84:87]
	v_mfma_f32_16x16x32_bf16 v[72:75], v[132:135], v[202:205], v[72:75]
	v_mfma_f32_16x16x32_bf16 v[68:71], v[166:169], v[202:205], v[68:71]
	v_mfma_f32_16x16x32_bf16 v[144:147], v[136:139], v[182:185], v[144:147]
	v_mfma_f32_16x16x32_bf16 v[140:143], v[170:173], v[182:185], v[140:143]
	v_mfma_f32_16x16x32_bf16 v[104:107], v[136:139], v[190:193], v[104:107]
	v_mfma_f32_16x16x32_bf16 v[100:103], v[170:173], v[190:193], v[100:103]
	v_mfma_f32_16x16x32_bf16 v[88:91], v[136:139], v[198:201], v[88:91]
	v_mfma_f32_16x16x32_bf16 v[84:87], v[170:173], v[198:201], v[84:87]
	v_mfma_f32_16x16x32_bf16 v[72:75], v[136:139], v[206:209], v[72:75]
	v_mfma_f32_16x16x32_bf16 v[68:71], v[170:173], v[206:209], v[68:71]
	s_barrier
; #define PG8_STAGE(bufoff, gbase, voff) do { _Pragma("unroll") for (int _i = 0; _i < 2; ++_i) \
;         __builtin_amdgcn_global_load_lds((const unsigned*)((const char*)(gbase) + (voff)[_i]), (PG8_LAS unsigned*)(lds + (bufoff) + ldsw + _i * 8192), 16, 0, 0); } while (0)
; #define PG8_LDA(dst, b, h) do { _Pragma("unroll") for (int m = 0; m < 4; ++m) _Pragma("unroll") for (int k = 0; k < 2; ++k) dst[m][k] = *(const PG8_LAS bf16x8*)(lds + PG8_SA(b, h) + aoff + m * 2048 + k * 1024); } while (0)
; #define PG8_MMA(ai, bj, At, Bt) do { __builtin_amdgcn_s_setprio(1); _Pragma("unroll") for (int m = 0; m < 4; ++m) _Pragma("unroll") for (int n = 0; n < 2; ++n) _Pragma("unroll") for (int k = 0; k < 2; ++k) \
;         acc[ai][bj][m][n] = __builtin_amdgcn_mfma_f32_16x16x32_bf16(Bt[n][k], At[m][k], acc[ai][bj][m][n], 0, 0, 0); __builtin_amdgcn_s_setprio(0); } while (0)
; #define PG8_WAIT_V(n) asm volatile("s_waitcnt vmcnt(" #n ")" ::: "memory")
; #define PG8_WAIT_L(n) asm volatile("s_waitcnt lgkmcnt(" #n ")" ::: "memory")
; #define PG8_BAR __builtin_amdgcn_s_barrier()
; #define PG8_SCHED __builtin_amdgcn_sched_barrier(0)
; template <class Epi, class Sched, bool ALIGN_EPI = false, bool SP2 = false>
; __device__ __forceinline__ void gemm_phase(PG8_LAS unsigned char* lds, const Gemm g, const Sched& S, const Epi& E) {
;     ...
;         for (int t = 0; t < nt; t += 2) {
;             const bool last = (t == nt - 2);
;             const char* a1 = cA + (size_t)(t + 1) * kstep;
;             const char* a2 = last ? nA : cA + (size_t)(t + 2) * kstep; const char* b2 = last ? nB : cB + (size_t)(t + 2) * kstep;
;     ...
;             PG8_LDA(At, 1, 1); PG8_STAGE(PG8_SB(1, 0), b3, voffB); PG8_STAGE(PG8_SB(1, 1), b3 + hstep, voffB); PG8_STAGE(PG8_SA(1, 0), a3, voffA);
;             PG8_WAIT_V(8); PG8_WAIT_L(0); PG8_BAR; PG8_MMA(1, 0, At, B0); PG8_MMA(1, 1, At, B1); PG8_BAR; PG8_SCHED;
	s_setprio 0
	s_add_i32 s26, s26, s46
	v_lshl_add_u64 v[210:211], v[210:211], 0, s[60:61]
	s_mov_b32 m0, s26
	ds_read_b128 v[174:177], v181 offset:49152
	ds_read_b128 v[182:185], v181 offset:50176
	ds_read_b128 v[186:189], v181 offset:51200
	ds_read_b128 v[190:193], v181 offset:52224
	ds_read_b128 v[194:197], v181 offset:53248
	ds_read_b128 v[198:201], v181 offset:54272
	ds_read_b128 v[202:205], v181 offset:55296
	ds_read_b128 v[206:209], v181 offset:56320
	global_load_lds_dwordx4 v[210:211], off
	s_add_i32 m0, s26, 0x2000
	s_add_u32 s42, s42, 0x80080
	v_lshl_add_u64 v[210:211], v[212:213], 0, s[60:61]
	s_addc_u32 s43, s43, 0
	s_add_i32 s26, s31, s46
	global_load_lds_dwordx4 v[210:211], off
	v_lshl_add_u64 v[210:211], s[42:43], 0, v[2:3]
	s_mov_b32 m0, s26
	s_nop 0
	global_load_lds_dwordx4 v[210:211], off
	v_lshl_add_u64 v[210:211], s[42:43], 0, v[156:157]
	s_add_i32 m0, s26, 0x2000
	s_nop 0
	global_load_lds_dwordx4 v[210:211], off
	v_lshl_add_u64 v[210:211], v[214:215], 0, s[60:61]
	s_mov_b32 m0, s54
	s_nop 0
	global_load_lds_dwordx4 v[210:211], off
	v_lshl_add_u64 v[210:211], v[216:217], 0, s[60:61]
	s_mov_b32 m0, s55
	s_nop 0
	global_load_lds_dwordx4 v[210:211], off
	s_waitcnt vmcnt(8)
	s_waitcnt lgkmcnt(0)
	s_setprio 1
	s_barrier
	v_mfma_f32_16x16x32_bf16 v[64:67], v[116:119], v[174:177], v[64:67]
	v_mfma_f32_16x16x32_bf16 v[60:63], v[124:127], v[174:177], v[60:63]
	v_mfma_f32_16x16x32_bf16 v[48:51], v[116:119], v[186:189], v[48:51]
	v_mfma_f32_16x16x32_bf16 v[44:47], v[124:127], v[186:189], v[44:47]
	v_mfma_f32_16x16x32_bf16 v[32:35], v[116:119], v[194:197], v[32:35]
	v_mfma_f32_16x16x32_bf16 v[28:31], v[124:127], v[194:197], v[28:31]
	v_mfma_f32_16x16x32_bf16 v[16:19], v[116:119], v[202:205], v[16:19]
	v_mfma_f32_16x16x32_bf16 v[12:15], v[124:127], v[202:205], v[12:15]
	v_mfma_f32_16x16x32_bf16 v[64:67], v[120:123], v[182:185], v[64:67]
	v_mfma_f32_16x16x32_bf16 v[60:63], v[128:131], v[182:185], v[60:63]
	v_mfma_f32_16x16x32_bf16 v[48:51], v[120:123], v[190:193], v[48:51]
	v_mfma_f32_16x16x32_bf16 v[44:47], v[128:131], v[190:193], v[44:47]
	v_mfma_f32_16x16x32_bf16 v[32:35], v[120:123], v[198:201], v[32:35]
	v_mfma_f32_16x16x32_bf16 v[28:31], v[128:131], v[198:201], v[28:31]
	v_mfma_f32_16x16x32_bf16 v[16:19], v[120:123], v[206:209], v[16:19]
	v_mfma_f32_16x16x32_bf16 v[12:15], v[128:131], v[206:209], v[12:15]
	s_setprio 0
	s_setprio 1
	v_mfma_f32_16x16x32_bf16 v[56:59], v[132:135], v[174:177], v[56:59]
	v_mfma_f32_16x16x32_bf16 v[52:55], v[166:169], v[174:177], v[52:55]
	v_mfma_f32_16x16x32_bf16 v[40:43], v[132:135], v[186:189], v[40:43]
	v_mfma_f32_16x16x32_bf16 v[36:39], v[166:169], v[186:189], v[36:39]
	v_mfma_f32_16x16x32_bf16 v[24:27], v[132:135], v[194:197], v[24:27]
	v_mfma_f32_16x16x32_bf16 v[20:23], v[166:169], v[194:197], v[20:23]
	v_mfma_f32_16x16x32_bf16 v[8:11], v[132:135], v[202:205], v[8:11]
	v_mfma_f32_16x16x32_bf16 v[4:7], v[166:169], v[202:205], v[4:7]
	v_mfma_f32_16x16x32_bf16 v[56:59], v[136:139], v[182:185], v[56:59]
	v_mfma_f32_16x16x32_bf16 v[52:55], v[170:173], v[182:185], v[52:55]
	v_mfma_f32_16x16x32_bf16 v[40:43], v[136:139], v[190:193], v[40:43]
	v_mfma_f32_16x16x32_bf16 v[36:39], v[170:173], v[190:193], v[36:39]
	v_mfma_f32_16x16x32_bf16 v[24:27], v[136:139], v[198:201], v[24:27]
	v_mfma_f32_16x16x32_bf16 v[20:23], v[170:173], v[198:201], v[20:23]
	v_mfma_f32_16x16x32_bf16 v[8:11], v[136:139], v[206:209], v[8:11]
	v_mfma_f32_16x16x32_bf16 v[4:7], v[170:173], v[206:209], v[4:7]
	s_barrier
	s_setprio 0
	s_add_i32 s66, s66, 2
	s_add_u32 s38, s38, 0x100
	s_addc_u32 s39, s39, 0
	s_add_u32 s63, s63, 0x100
	s_addc_u32 s64, s64, 0
	s_cmp_gt_u32 s66, 29
	s_cbranch_scc0 .LBB0_1961
	s_and_b64 vcc, exec, s[16:17]
	s_cbranch_vccz .LBB0_1964
	s_barrier

; #define PG8_STAGE(bufoff, gbase, voff) do { _Pragma("unroll") for (int _i = 0; _i < 2; ++_i) \
;         __builtin_amdgcn_global_load_lds((const unsigned*)((const char*)(gbase) + (voff)[_i]), (PG8_LAS unsigned*)(lds + (bufoff) + ldsw + _i * 8192), 16, 0, 0); } while (0)
; #define PG8_LDA(dst, b, h) do { _Pragma("unroll") for (int m = 0; m < 4; ++m) _Pragma("unroll") for (int k = 0; k < 2; ++k) dst[m][k] = *(const PG8_LAS bf16x8*)(lds + PG8_SA(b, h) + aoff + m * 2048 + k * 1024); } while (0)
; #define PG8_LDB(dst, b, h) do { _Pragma("unroll") for (int n = 0; n < 2; ++n) _Pragma("unroll") for (int k = 0; k < 2; ++k) dst[n][k] = *(const PG8_LAS bf16x8*)(lds + PG8_SB(b, h) + boff + n * 2048 + k * 1024); } while (0)
; #define PG8_MMA(ai, bj, At, Bt) do { __builtin_amdgcn_s_setprio(1); _Pragma("unroll") for (int m = 0; m < 4; ++m) _Pragma("unroll") for (int n = 0; n < 2; ++n) _Pragma("unroll") for (int k = 0; k < 2; ++k) \
;         acc[ai][bj][m][n] = __builtin_amdgcn_mfma_f32_16x16x32_bf16(Bt[n][k], At[m][k], acc[ai][bj][m][n], 0, 0, 0); __builtin_amdgcn_s_setprio(0); } while (0)
; #define PG8_WAIT_V(n) asm volatile("s_waitcnt vmcnt(" #n ")" ::: "memory")
; #define PG8_WAIT_L(n) asm volatile("s_waitcnt lgkmcnt(" #n ")" ::: "memory")
; #define PG8_BAR __builtin_amdgcn_s_barrier()
; #define PG8_SCHED __builtin_amdgcn_sched_barrier(0)
; template <class Epi, class Sched, bool ALIGN_EPI = false, bool SP2 = false>
; __device__ __forceinline__ void gemm_phase(PG8_LAS unsigned char* lds, const Gemm g, const Sched& S, const Epi& E) {
;     ...
;             PG8_LDB(B0, 0, 0); PG8_LDB(B1, 0, 1); PG8_SCHED; PG8_LDA(At, 0, 0); PG8_STAGE(PG8_SA(1, 1), a1 + hstep, voffA);
;             PG8_WAIT_V(8); PG8_WAIT_L(0); PG8_BAR; PG8_MMA(0, 0, At, B0); PG8_MMA(0, 1, At, B1); PG8_BAR; PG8_SCHED;
;             PG8_LDA(At, 0, 1); PG8_STAGE(PG8_SB(0, 0), b2, voffB); PG8_STAGE(PG8_SB(0, 1), b2 + hstep, voffB); PG8_STAGE(PG8_SA(0, 0), a2, voffA);
;             PG8_WAIT_V(8); PG8_WAIT_L(0); PG8_BAR; PG8_MMA(1, 0, At, B0); PG8_MMA(1, 1, At, B1); PG8_BAR; PG8_SCHED;
.LBB0_2104:
	s_add_u32 s26, s34, 0xfff80080
	s_addc_u32 s31, s35, -1
	s_add_i32 s57, 0, 0x10000
	s_cmp_eq_u32 s56, 28
	s_cselect_b32 s39, s17, s31
	s_cselect_b32 s38, s52, s26
	v_add_u32_e32 v149, s57, v146
	s_cselect_b32 s37, s15, s55
	s_cselect_b32 s36, s53, s54
	s_add_i32 s26, 0, 0x14000
	ds_read_b128 v[142:145], v149
	ds_read_b128 v[150:153], v149 offset:1024
	ds_read_b128 v[154:157], v149 offset:2048
	ds_read_b128 v[158:161], v149 offset:3072
	v_add_u32_e32 v149, s26, v146
	ds_read_b128 v[162:165], v149
	ds_read_b128 v[166:169], v149 offset:1024
	ds_read_b128 v[170:173], v149 offset:2048
	ds_read_b128 v[174:177], v149 offset:3072
	v_lshl_add_u64 v[178:179], s[34:35], 0, v[138:139]
	s_add_i32 m0, s43, 0xc000
	ds_read_b128 v[182:185], v148
	ds_read_b128 v[186:189], v148 offset:1024
	ds_read_b128 v[190:193], v148 offset:2048
	ds_read_b128 v[194:197], v148 offset:3072
	ds_read_b128 v[198:201], v148 offset:4096
	ds_read_b128 v[202:205], v148 offset:5120
	ds_read_b128 v[206:209], v148 offset:6144
	ds_read_b128 v[210:213], v148 offset:7168
	global_load_lds_dwordx4 v[178:179], off
	v_lshl_add_u64 v[178:179], s[34:35], 0, v[140:141]
	s_add_i32 m0, s43, 0xe000
	s_nop 0
	global_load_lds_dwordx4 v[178:179], off
	s_waitcnt vmcnt(8)
	s_waitcnt lgkmcnt(0)
	s_setprio 1
	s_barrier
	v_mfma_f32_16x16x32_bf16 v[128:131], v[142:145], v[182:185], v[128:131]
	v_mfma_f32_16x16x32_bf16 v[124:127], v[154:157], v[182:185], v[124:127]
	v_mfma_f32_16x16x32_bf16 v[112:115], v[142:145], v[190:193], v[112:115]
	v_mfma_f32_16x16x32_bf16 v[108:111], v[154:157], v[190:193], v[108:111]
	v_mfma_f32_16x16x32_bf16 v[96:99], v[142:145], v[198:201], v[96:99]
	v_mfma_f32_16x16x32_bf16 v[92:95], v[154:157], v[198:201], v[92:95]
	v_mfma_f32_16x16x32_bf16 v[80:83], v[142:145], v[206:209], v[80:83]
	v_mfma_f32_16x16x32_bf16 v[76:79], v[154:157], v[206:209], v[76:79]
	v_mfma_f32_16x16x32_bf16 v[128:131], v[150:153], v[186:189], v[128:131]
	v_mfma_f32_16x16x32_bf16 v[124:127], v[158:161], v[186:189], v[124:127]
	v_mfma_f32_16x16x32_bf16 v[112:115], v[150:153], v[194:197], v[112:115]
	v_mfma_f32_16x16x32_bf16 v[108:111], v[158:161], v[194:197], v[108:111]
	v_mfma_f32_16x16x32_bf16 v[96:99], v[150:153], v[202:205], v[96:99]
	v_mfma_f32_16x16x32_bf16 v[92:95], v[158:161], v[202:205], v[92:95]
	v_mfma_f32_16x16x32_bf16 v[80:83], v[150:153], v[210:213], v[80:83]
	v_mfma_f32_16x16x32_bf16 v[76:79], v[158:161], v[210:213], v[76:79]
	s_setprio 0
	s_setprio 1
	v_mfma_f32_16x16x32_bf16 v[120:123], v[162:165], v[182:185], v[120:123]
	v_mfma_f32_16x16x32_bf16 v[116:119], v[170:173], v[182:185], v[116:119]
	v_mfma_f32_16x16x32_bf16 v[104:107], v[162:165], v[190:193], v[104:107]
	v_mfma_f32_16x16x32_bf16 v[100:103], v[170:173], v[190:193], v[100:103]
	v_mfma_f32_16x16x32_bf16 v[88:91], v[162:165], v[198:201], v[88:91]
	v_mfma_f32_16x16x32_bf16 v[84:87], v[170:173], v[198:201], v[84:87]
	v_mfma_f32_16x16x32_bf16 v[72:75], v[162:165], v[206:209], v[72:75]
	v_mfma_f32_16x16x32_bf16 v[68:71], v[170:173], v[206:209], v[68:71]
	v_mfma_f32_16x16x32_bf16 v[120:123], v[166:169], v[186:189], v[120:123]
	v_mfma_f32_16x16x32_bf16 v[116:119], v[174:177], v[186:189], v[116:119]
	v_mfma_f32_16x16x32_bf16 v[104:107], v[166:169], v[194:197], v[104:107]
	v_mfma_f32_16x16x32_bf16 v[100:103], v[174:177], v[194:197], v[100:103]
	v_mfma_f32_16x16x32_bf16 v[88:91], v[166:169], v[202:205], v[88:91]
	v_mfma_f32_16x16x32_bf16 v[84:87], v[174:177], v[202:205], v[84:87]
	v_mfma_f32_16x16x32_bf16 v[72:75], v[166:169], v[210:213], v[72:75]
	v_mfma_f32_16x16x32_bf16 v[68:71], v[174:177], v[210:213], v[68:71]
	s_barrier
	s_setprio 0
	s_add_i32 s31, s57, s42
	v_lshl_add_u64 v[178:179], s[36:37], 0, v[2:3]
	s_mov_b32 m0, s31
	ds_read_b128 v[182:185], v148 offset:16384
	ds_read_b128 v[186:189], v148 offset:17408
	ds_read_b128 v[190:193], v148 offset:18432
	ds_read_b128 v[194:197], v148 offset:19456
	ds_read_b128 v[198:201], v148 offset:20480
	ds_read_b128 v[202:205], v148 offset:21504
	ds_read_b128 v[206:209], v148 offset:22528
	ds_read_b128 v[210:213], v148 offset:23552
	global_load_lds_dwordx4 v[178:179], off
	s_add_i32 m0, s31, 0x2000
	s_add_u32 s62, s36, 0x80000
	v_lshl_add_u64 v[214:215], s[36:37], 0, v[132:133]
	s_addc_u32 s63, s37, 0
	s_add_i32 s26, s26, s42
	global_load_lds_dwordx4 v[214:215], off
	v_lshl_add_u64 v[216:217], s[62:63], 0, v[2:3]
	s_mov_b32 m0, s26
	v_lshl_add_u64 v[218:219], s[38:39], 0, v[134:135]
	global_load_lds_dwordx4 v[216:217], off
	v_lshl_add_u64 v[216:217], s[62:63], 0, v[132:133]
	s_add_i32 m0, s26, 0x2000
	s_nop 0
	global_load_lds_dwordx4 v[216:217], off
	v_lshl_add_u64 v[216:217], s[38:39], 0, v[136:137]
	s_mov_b32 m0, s43
	s_nop 0
	global_load_lds_dwordx4 v[216:217], off
	s_mov_b32 m0, s44
	s_nop 0
	global_load_lds_dwordx4 v[218:219], off
	s_waitcnt vmcnt(8)
	s_waitcnt lgkmcnt(0)
	s_setprio 1
	s_barrier
; #define PG8_STAGE(bufoff, gbase, voff) do { _Pragma("unroll") for (int _i = 0; _i < 2; ++_i) \
;         __builtin_amdgcn_global_load_lds((const unsigned*)((const char*)(gbase) + (voff)[_i]), (PG8_LAS unsigned*)(lds + (bufoff) + ldsw + _i * 8192), 16, 0, 0); } while (0)
; #define PG8_LDA(dst, b, h) do { _Pragma("unroll") for (int m = 0; m < 4; ++m) _Pragma("unroll") for (int k = 0; k < 2; ++k) dst[m][k] = *(const PG8_LAS bf16x8*)(lds + PG8_SA(b, h) + aoff + m * 2048 + k * 1024); } while (0)
; #define PG8_LDB(dst, b, h) do { _Pragma("unroll") for (int n = 0; n < 2; ++n) _Pragma("unroll") for (int k = 0; k < 2; ++k) dst[n][k] = *(const PG8_LAS bf16x8*)(lds + PG8_SB(b, h) + boff + n * 2048 + k * 1024); } while (0)
; #define PG8_MMA(ai, bj, At, Bt) do { __builtin_amdgcn_s_setprio(1); _Pragma("unroll") for (int m = 0; m < 4; ++m) _Pragma("unroll") for (int n = 0; n < 2; ++n) _Pragma("unroll") for (int k = 0; k < 2; ++k) \
;         acc[ai][bj][m][n] = __builtin_amdgcn_mfma_f32_16x16x32_bf16(Bt[n][k], At[m][k], acc[ai][bj][m][n], 0, 0, 0); __builtin_amdgcn_s_setprio(0); } while (0)
; #define PG8_WAIT_V(n) asm volatile("s_waitcnt vmcnt(" #n ")" ::: "memory")
; #define PG8_WAIT_L(n) asm volatile("s_waitcnt lgkmcnt(" #n ")" ::: "memory")
; #define PG8_BAR __builtin_amdgcn_s_barrier()
; #define PG8_SCHED __builtin_amdgcn_sched_barrier(0)
; template <class Epi, class Sched, bool ALIGN_EPI = false, bool SP2 = false>
; __device__ __forceinline__ void gemm_phase(PG8_LAS unsigned char* lds, const Gemm g, const Sched& S, const Epi& E) {
;     ...
;             PG8_WAIT_V(8); PG8_WAIT_L(0); PG8_BAR; PG8_MMA(1, 0, At, B0); PG8_MMA(1, 1, At, B1); PG8_BAR; PG8_SCHED;
;             PG8_LDB(B0, 1, 0); PG8_LDB(B1, 1, 1); PG8_SCHED; PG8_LDA(At, 1, 0); PG8_STAGE(PG8_SA(0, 1), a2 + hstep, voffA);
;             PG8_WAIT_V(8); PG8_WAIT_L(0); PG8_BAR; PG8_MMA(0, 0, At, B0); PG8_MMA(0, 1, At, B1); PG8_BAR; PG8_SCHED;
	v_mfma_f32_16x16x32_bf16 v[64:67], v[142:145], v[182:185], v[64:67]
	v_mfma_f32_16x16x32_bf16 v[60:63], v[154:157], v[182:185], v[60:63]
	v_mfma_f32_16x16x32_bf16 v[48:51], v[142:145], v[190:193], v[48:51]
	v_mfma_f32_16x16x32_bf16 v[44:47], v[154:157], v[190:193], v[44:47]
	v_mfma_f32_16x16x32_bf16 v[32:35], v[142:145], v[198:201], v[32:35]
	v_mfma_f32_16x16x32_bf16 v[28:31], v[154:157], v[198:201], v[28:31]
	v_mfma_f32_16x16x32_bf16 v[16:19], v[142:145], v[206:209], v[16:19]
	v_mfma_f32_16x16x32_bf16 v[12:15], v[154:157], v[206:209], v[12:15]
	v_mfma_f32_16x16x32_bf16 v[64:67], v[150:153], v[186:189], v[64:67]
	v_mfma_f32_16x16x32_bf16 v[60:63], v[158:161], v[186:189], v[60:63]
	v_mfma_f32_16x16x32_bf16 v[48:51], v[150:153], v[194:197], v[48:51]
	v_mfma_f32_16x16x32_bf16 v[44:47], v[158:161], v[194:197], v[44:47]
	v_mfma_f32_16x16x32_bf16 v[32:35], v[150:153], v[202:205], v[32:35]
	v_mfma_f32_16x16x32_bf16 v[28:31], v[158:161], v[202:205], v[28:31]
	v_mfma_f32_16x16x32_bf16 v[16:19], v[150:153], v[210:213], v[16:19]
	v_mfma_f32_16x16x32_bf16 v[12:15], v[158:161], v[210:213], v[12:15]
	s_setprio 0
	s_setprio 1
	v_mfma_f32_16x16x32_bf16 v[56:59], v[162:165], v[182:185], v[56:59]
	v_mfma_f32_16x16x32_bf16 v[52:55], v[170:173], v[182:185], v[52:55]
	v_mfma_f32_16x16x32_bf16 v[40:43], v[162:165], v[190:193], v[40:43]
	v_mfma_f32_16x16x32_bf16 v[36:39], v[170:173], v[190:193], v[36:39]
	v_mfma_f32_16x16x32_bf16 v[24:27], v[162:165], v[198:201], v[24:27]
	v_mfma_f32_16x16x32_bf16 v[20:23], v[170:173], v[198:201], v[20:23]
	v_mfma_f32_16x16x32_bf16 v[8:11], v[162:165], v[206:209], v[8:11]
	v_mfma_f32_16x16x32_bf16 v[4:7], v[170:173], v[206:209], v[4:7]
	v_mfma_f32_16x16x32_bf16 v[56:59], v[166:169], v[186:189], v[56:59]
	v_mfma_f32_16x16x32_bf16 v[52:55], v[174:177], v[186:189], v[52:55]
	v_mfma_f32_16x16x32_bf16 v[40:43], v[166:169], v[194:197], v[40:43]
	v_mfma_f32_16x16x32_bf16 v[36:39], v[174:177], v[194:197], v[36:39]
	v_mfma_f32_16x16x32_bf16 v[24:27], v[166:169], v[202:205], v[24:27]
	v_mfma_f32_16x16x32_bf16 v[20:23], v[174:177], v[202:205], v[20:23]
	v_mfma_f32_16x16x32_bf16 v[8:11], v[166:169], v[210:213], v[8:11]
	v_mfma_f32_16x16x32_bf16 v[4:7], v[174:177], v[210:213], v[4:7]
	s_barrier
	s_setprio 0
	s_add_i32 s26, 0, 0x18000
	v_add_u32_e32 v149, s26, v146
	s_add_i32 s31, 0, 0x1c000
	ds_read_b128 v[142:145], v149
	ds_read_b128 v[150:153], v149 offset:1024
	ds_read_b128 v[154:157], v149 offset:2048
	ds_read_b128 v[158:161], v149 offset:3072
	v_add_u32_e32 v149, s31, v146
	ds_read_b128 v[162:165], v149
	ds_read_b128 v[166:169], v149 offset:1024
	ds_read_b128 v[170:173], v149 offset:2048
	ds_read_b128 v[174:177], v149 offset:3072
	s_add_u32 s38, s38, 0x80000
	s_addc_u32 s39, s39, 0
	s_mov_b32 m0, s45
	v_lshl_add_u64 v[220:221], s[38:39], 0, v[136:137]
	ds_read_b128 v[182:185], v148 offset:32768
	ds_read_b128 v[186:189], v148 offset:33792
	ds_read_b128 v[190:193], v148 offset:34816
	ds_read_b128 v[194:197], v148 offset:35840
	ds_read_b128 v[198:201], v148 offset:36864
	ds_read_b128 v[202:205], v148 offset:37888
	ds_read_b128 v[206:209], v148 offset:38912
	ds_read_b128 v[210:213], v148 offset:39936
	global_load_lds_dwordx4 v[220:221], off
	v_lshl_add_u64 v[220:221], s[38:39], 0, v[134:135]
	s_mov_b32 m0, s46
	s_nop 0
	global_load_lds_dwordx4 v[220:221], off
	s_waitcnt vmcnt(8)
	s_waitcnt lgkmcnt(0)
	s_setprio 1
	s_barrier
	v_mfma_f32_16x16x32_bf16 v[128:131], v[142:145], v[182:185], v[128:131]
	v_mfma_f32_16x16x32_bf16 v[124:127], v[154:157], v[182:185], v[124:127]
	v_mfma_f32_16x16x32_bf16 v[112:115], v[142:145], v[190:193], v[112:115]
	v_mfma_f32_16x16x32_bf16 v[108:111], v[154:157], v[190:193], v[108:111]
	v_mfma_f32_16x16x32_bf16 v[96:99], v[142:145], v[198:201], v[96:99]
	v_mfma_f32_16x16x32_bf16 v[92:95], v[154:157], v[198:201], v[92:95]
	v_mfma_f32_16x16x32_bf16 v[80:83], v[142:145], v[206:209], v[80:83]
	v_mfma_f32_16x16x32_bf16 v[76:79], v[154:157], v[206:209], v[76:79]
	v_mfma_f32_16x16x32_bf16 v[128:131], v[150:153], v[186:189], v[128:131]
	v_mfma_f32_16x16x32_bf16 v[124:127], v[158:161], v[186:189], v[124:127]
	v_mfma_f32_16x16x32_bf16 v[112:115], v[150:153], v[194:197], v[112:115]
	v_mfma_f32_16x16x32_bf16 v[108:111], v[158:161], v[194:197], v[108:111]
	v_mfma_f32_16x16x32_bf16 v[96:99], v[150:153], v[202:205], v[96:99]
	v_mfma_f32_16x16x32_bf16 v[92:95], v[158:161], v[202:205], v[92:95]
	v_mfma_f32_16x16x32_bf16 v[80:83], v[150:153], v[210:213], v[80:83]
	v_mfma_f32_16x16x32_bf16 v[76:79], v[158:161], v[210:213], v[76:79]
	s_setprio 0
	s_setprio 1
	v_mfma_f32_16x16x32_bf16 v[120:123], v[162:165], v[182:185], v[120:123]
	v_mfma_f32_16x16x32_bf16 v[116:119], v[170:173], v[182:185], v[116:119]
	v_mfma_f32_16x16x32_bf16 v[104:107], v[162:165], v[190:193], v[104:107]
	v_mfma_f32_16x16x32_bf16 v[100:103], v[170:173], v[190:193], v[100:103]
	v_mfma_f32_16x16x32_bf16 v[88:91], v[162:165], v[198:201], v[88:91]
	v_mfma_f32_16x16x32_bf16 v[84:87], v[170:173], v[198:201], v[84:87]
	v_mfma_f32_16x16x32_bf16 v[72:75], v[162:165], v[206:209], v[72:75]
	v_mfma_f32_16x16x32_bf16 v[68:71], v[170:173], v[206:209], v[68:71]
	v_mfma_f32_16x16x32_bf16 v[120:123], v[166:169], v[186:189], v[120:123]
	v_mfma_f32_16x16x32_bf16 v[116:119], v[174:177], v[186:189], v[116:119]
	v_mfma_f32_16x16x32_bf16 v[104:107], v[166:169], v[194:197], v[104:107]
	v_mfma_f32_16x16x32_bf16 v[100:103], v[174:177], v[194:197], v[100:103]
	v_mfma_f32_16x16x32_bf16 v[88:91], v[166:169], v[202:205], v[88:91]
	v_mfma_f32_16x16x32_bf16 v[84:87], v[174:177], v[202:205], v[84:87]
	v_mfma_f32_16x16x32_bf16 v[72:75], v[166:169], v[210:213], v[72:75]
	v_mfma_f32_16x16x32_bf16 v[68:71], v[174:177], v[210:213], v[68:71]
	s_barrier
; #define PG8_STAGE(bufoff, gbase, voff) do { _Pragma("unroll") for (int _i = 0; _i < 2; ++_i) \
;         __builtin_amdgcn_global_load_lds((const unsigned*)((const char*)(gbase) + (voff)[_i]), (PG8_LAS unsigned*)(lds + (bufoff) + ldsw + _i * 8192), 16, 0, 0); } while (0)
; #define PG8_LDA(dst, b, h) do { _Pragma("unroll") for (int m = 0; m < 4; ++m) _Pragma("unroll") for (int k = 0; k < 2; ++k) dst[m][k] = *(const PG8_LAS bf16x8*)(lds + PG8_SA(b, h) + aoff + m * 2048 + k * 1024); } while (0)
; #define PG8_MMA(ai, bj, At, Bt) do { __builtin_amdgcn_s_setprio(1); _Pragma("unroll") for (int m = 0; m < 4; ++m) _Pragma("unroll") for (int n = 0; n < 2; ++n) _Pragma("unroll") for (int k = 0; k < 2; ++k) \
;         acc[ai][bj][m][n] = __builtin_amdgcn_mfma_f32_16x16x32_bf16(Bt[n][k], At[m][k], acc[ai][bj][m][n], 0, 0, 0); __builtin_amdgcn_s_setprio(0); } while (0)
; #define PG8_WAIT_V(n) asm volatile("s_waitcnt vmcnt(" #n ")" ::: "memory")
; #define PG8_WAIT_L(n) asm volatile("s_waitcnt lgkmcnt(" #n ")" ::: "memory")
; #define PG8_BAR __builtin_amdgcn_s_barrier()
; #define PG8_SCHED __builtin_amdgcn_sched_barrier(0)
; template <class Epi, class Sched, bool ALIGN_EPI = false, bool SP2 = false>
; __device__ __forceinline__ void gemm_phase(PG8_LAS unsigned char* lds, const Gemm g, const Sched& S, const Epi& E) {
;     ...
;         for (int t = 0; t < nt; t += 2) {
;             const bool last = (t == nt - 2);
;             const char* a1 = cA + (size_t)(t + 1) * kstep;
;             const char* a2 = last ? nA : cA + (size_t)(t + 2) * kstep; const char* b2 = last ? nB : cB + (size_t)(t + 2) * kstep;
;     ...
;             PG8_LDA(At, 1, 1); PG8_STAGE(PG8_SB(1, 0), b3, voffB); PG8_STAGE(PG8_SB(1, 1), b3 + hstep, voffB); PG8_STAGE(PG8_SA(1, 0), a3, voffA);
;             PG8_WAIT_V(8); PG8_WAIT_L(0); PG8_BAR; PG8_MMA(1, 0, At, B0); PG8_MMA(1, 1, At, B1); PG8_BAR; PG8_SCHED;
	s_setprio 0
	s_add_i32 s26, s26, s42
	v_lshl_add_u64 v[178:179], v[178:179], 0, s[60:61]
	s_mov_b32 m0, s26
	ds_read_b128 v[182:185], v148 offset:49152
	ds_read_b128 v[186:189], v148 offset:50176
	ds_read_b128 v[190:193], v148 offset:51200
	ds_read_b128 v[194:197], v148 offset:52224
	ds_read_b128 v[198:201], v148 offset:53248
	ds_read_b128 v[202:205], v148 offset:54272
	ds_read_b128 v[206:209], v148 offset:55296
	ds_read_b128 v[210:213], v148 offset:56320
	global_load_lds_dwordx4 v[178:179], off
	s_add_i32 m0, s26, 0x2000
	s_add_u32 s36, s36, 0x80080
	v_lshl_add_u64 v[178:179], v[214:215], 0, s[60:61]
	s_addc_u32 s37, s37, 0
	s_add_i32 s26, s31, s42
	global_load_lds_dwordx4 v[178:179], off
	v_lshl_add_u64 v[178:179], s[36:37], 0, v[2:3]
	s_mov_b32 m0, s26
	s_nop 0
	global_load_lds_dwordx4 v[178:179], off
	v_lshl_add_u64 v[178:179], s[36:37], 0, v[132:133]
	s_add_i32 m0, s26, 0x2000
	s_nop 0
	global_load_lds_dwordx4 v[178:179], off
	v_lshl_add_u64 v[178:179], v[216:217], 0, s[60:61]
	s_mov_b32 m0, s47
	s_nop 0
	global_load_lds_dwordx4 v[178:179], off
	v_lshl_add_u64 v[178:179], v[218:219], 0, s[60:61]
	s_mov_b32 m0, s50
	s_nop 0
	global_load_lds_dwordx4 v[178:179], off
	s_waitcnt vmcnt(8)
	s_waitcnt lgkmcnt(0)
	s_setprio 1
	s_barrier
	v_mfma_f32_16x16x32_bf16 v[64:67], v[142:145], v[182:185], v[64:67]
	v_mfma_f32_16x16x32_bf16 v[60:63], v[154:157], v[182:185], v[60:63]
	v_mfma_f32_16x16x32_bf16 v[48:51], v[142:145], v[190:193], v[48:51]
	v_mfma_f32_16x16x32_bf16 v[44:47], v[154:157], v[190:193], v[44:47]
	v_mfma_f32_16x16x32_bf16 v[32:35], v[142:145], v[198:201], v[32:35]
	v_mfma_f32_16x16x32_bf16 v[28:31], v[154:157], v[198:201], v[28:31]
	v_mfma_f32_16x16x32_bf16 v[16:19], v[142:145], v[206:209], v[16:19]
	v_mfma_f32_16x16x32_bf16 v[12:15], v[154:157], v[206:209], v[12:15]
	v_mfma_f32_16x16x32_bf16 v[64:67], v[150:153], v[186:189], v[64:67]
	v_mfma_f32_16x16x32_bf16 v[60:63], v[158:161], v[186:189], v[60:63]
	v_mfma_f32_16x16x32_bf16 v[48:51], v[150:153], v[194:197], v[48:51]
	v_mfma_f32_16x16x32_bf16 v[44:47], v[158:161], v[194:197], v[44:47]
	v_mfma_f32_16x16x32_bf16 v[32:35], v[150:153], v[202:205], v[32:35]
	v_mfma_f32_16x16x32_bf16 v[28:31], v[158:161], v[202:205], v[28:31]
	v_mfma_f32_16x16x32_bf16 v[16:19], v[150:153], v[210:213], v[16:19]
	v_mfma_f32_16x16x32_bf16 v[12:15], v[158:161], v[210:213], v[12:15]
	s_setprio 0
	s_setprio 1
	v_mfma_f32_16x16x32_bf16 v[56:59], v[162:165], v[182:185], v[56:59]
	v_mfma_f32_16x16x32_bf16 v[52:55], v[170:173], v[182:185], v[52:55]
	v_mfma_f32_16x16x32_bf16 v[40:43], v[162:165], v[190:193], v[40:43]
	v_mfma_f32_16x16x32_bf16 v[36:39], v[170:173], v[190:193], v[36:39]
	v_mfma_f32_16x16x32_bf16 v[24:27], v[162:165], v[198:201], v[24:27]
	v_mfma_f32_16x16x32_bf16 v[20:23], v[170:173], v[198:201], v[20:23]
	v_mfma_f32_16x16x32_bf16 v[8:11], v[162:165], v[206:209], v[8:11]
	v_mfma_f32_16x16x32_bf16 v[4:7], v[170:173], v[206:209], v[4:7]
	v_mfma_f32_16x16x32_bf16 v[56:59], v[166:169], v[186:189], v[56:59]
	v_mfma_f32_16x16x32_bf16 v[52:55], v[174:177], v[186:189], v[52:55]
	v_mfma_f32_16x16x32_bf16 v[40:43], v[166:169], v[194:197], v[40:43]
	v_mfma_f32_16x16x32_bf16 v[36:39], v[174:177], v[194:197], v[36:39]
	v_mfma_f32_16x16x32_bf16 v[24:27], v[166:169], v[202:205], v[24:27]
	v_mfma_f32_16x16x32_bf16 v[20:23], v[174:177], v[202:205], v[20:23]
	v_mfma_f32_16x16x32_bf16 v[8:11], v[166:169], v[210:213], v[8:11]
	v_mfma_f32_16x16x32_bf16 v[4:7], v[174:177], v[210:213], v[4:7]
	s_barrier
	s_setprio 0
	s_add_i32 s56, s56, 2
	s_add_u32 s34, s34, 0x100
	s_addc_u32 s35, s35, 0
	s_add_u32 s54, s54, 0x100
	s_addc_u32 s55, s55, 0
	s_cmp_gt_u32 s56, 29
	s_cbranch_scc0 .LBB0_2104
	s_and_b64 vcc, exec, s[12:13]
	s_cbranch_vccz .LBB0_2107
	s_barrier

; #define PG8_STAGE(bufoff, gbase, voff) do { _Pragma("unroll") for (int _i = 0; _i < 2; ++_i) \
;         __builtin_amdgcn_global_load_lds((const unsigned*)((const char*)(gbase) + (voff)[_i]), (PG8_LAS unsigned*)(lds + (bufoff) + ldsw + _i * 8192), 16, 0, 0); } while (0)
; #define PG8_LDA(dst, b, h) do { _Pragma("unroll") for (int m = 0; m < 4; ++m) _Pragma("unroll") for (int k = 0; k < 2; ++k) dst[m][k] = *(const PG8_LAS bf16x8*)(lds + PG8_SA(b, h) + aoff + m * 2048 + k * 1024); } while (0)
; #define PG8_LDB(dst, b, h) do { _Pragma("unroll") for (int n = 0; n < 2; ++n) _Pragma("unroll") for (int k = 0; k < 2; ++k) dst[n][k] = *(const PG8_LAS bf16x8*)(lds + PG8_SB(b, h) + boff + n * 2048 + k * 1024); } while (0)
; #define PG8_MMA(ai, bj, At, Bt) do { __builtin_amdgcn_s_setprio(1); _Pragma("unroll") for (int m = 0; m < 4; ++m) _Pragma("unroll") for (int n = 0; n < 2; ++n) _Pragma("unroll") for (int k = 0; k < 2; ++k) \
;         acc[ai][bj][m][n] = __builtin_amdgcn_mfma_f32_16x16x32_bf16(Bt[n][k], At[m][k], acc[ai][bj][m][n], 0, 0, 0); __builtin_amdgcn_s_setprio(0); } while (0)
; #define PG8_WAIT_V(n) asm volatile("s_waitcnt vmcnt(" #n ")" ::: "memory")
; #define PG8_WAIT_L(n) asm volatile("s_waitcnt lgkmcnt(" #n ")" ::: "memory")
; #define PG8_BAR __builtin_amdgcn_s_barrier()
; #define PG8_SCHED __builtin_amdgcn_sched_barrier(0)
; template <class Epi, class Sched, bool ALIGN_EPI = false, bool SP2 = false>
; __device__ __forceinline__ void gemm_phase(PG8_LAS unsigned char* lds, const Gemm g, const Sched& S, const Epi& E) {
;     ...
;             PG8_LDB(B0, 0, 0); PG8_LDB(B1, 0, 1); PG8_SCHED; PG8_LDA(At, 0, 0); PG8_STAGE(PG8_SA(1, 1), a1 + hstep, voffA);
;             PG8_WAIT_V(8); PG8_WAIT_L(0); PG8_BAR; PG8_MMA(0, 0, At, B0); PG8_MMA(0, 1, At, B1); PG8_BAR; PG8_SCHED;
;             PG8_LDA(At, 0, 1); PG8_STAGE(PG8_SB(0, 0), b2, voffB); PG8_STAGE(PG8_SB(0, 1), b2 + hstep, voffB); PG8_STAGE(PG8_SA(0, 0), a2, voffA);
;             PG8_WAIT_V(8); PG8_WAIT_L(0); PG8_BAR; PG8_MMA(1, 0, At, B0); PG8_MMA(1, 1, At, B1); PG8_BAR; PG8_SCHED;
.LBB0_2176:
	s_add_u32 s26, s6, 0xffe00080
	s_addc_u32 s31, s7, -1
	s_add_i32 s67, 0, 0x10000
	s_cmpk_eq_i32 s74, 0x7c
	s_cselect_b32 s47, s30, s31
	s_cselect_b32 s46, s37, s26
	s_cselect_b32 s45, s35, s70
	s_cselect_b32 s44, s64, s66
	s_add_i32 s26, 0, 0x14000
	v_add_u32_e32 v144, s67, v181
	v_add_u32_e32 v170, s26, v181
	ds_read_b128 v[124:127], v144
	ds_read_b128 v[136:139], v144 offset:1024
	ds_read_b128 v[140:143], v144 offset:2048
	ds_read_b128 v[144:147], v144 offset:3072
	ds_read_b128 v[148:151], v170
	ds_read_b128 v[152:155], v170 offset:1024
	ds_read_b128 v[156:159], v170 offset:2048
	ds_read_b128 v[170:173], v170 offset:3072
	v_lshl_add_u64 v[178:179], s[6:7], 0, v[166:167]
	s_add_i32 m0, s51, 0xc000
	ds_read_b128 v[174:177], v183
	ds_read_b128 v[184:187], v183 offset:1024
	ds_read_b128 v[188:191], v183 offset:2048
	ds_read_b128 v[192:195], v183 offset:3072
	ds_read_b128 v[196:199], v183 offset:4096
	ds_read_b128 v[200:203], v183 offset:5120
	ds_read_b128 v[204:207], v183 offset:6144
	ds_read_b128 v[208:211], v183 offset:7168
	global_load_lds_dwordx4 v[178:179], off
	v_lshl_add_u64 v[178:179], s[6:7], 0, v[168:169]
	s_add_i32 m0, s51, 0xe000
	s_nop 0
	global_load_lds_dwordx4 v[178:179], off
	s_waitcnt vmcnt(8)
	s_waitcnt lgkmcnt(0)
	s_setprio 1
	s_barrier
	v_mfma_f32_16x16x32_bf16 v[132:135], v[124:127], v[174:177], v[132:135]
	v_mfma_f32_16x16x32_bf16 v[128:131], v[140:143], v[174:177], v[128:131]
	v_mfma_f32_16x16x32_bf16 v[112:115], v[124:127], v[188:191], v[112:115]
	v_mfma_f32_16x16x32_bf16 v[108:111], v[140:143], v[188:191], v[108:111]
	v_mfma_f32_16x16x32_bf16 v[96:99], v[124:127], v[196:199], v[96:99]
	v_mfma_f32_16x16x32_bf16 v[92:95], v[140:143], v[196:199], v[92:95]
	v_mfma_f32_16x16x32_bf16 v[80:83], v[124:127], v[204:207], v[80:83]
	v_mfma_f32_16x16x32_bf16 v[76:79], v[140:143], v[204:207], v[76:79]
	v_mfma_f32_16x16x32_bf16 v[132:135], v[136:139], v[184:187], v[132:135]
	v_mfma_f32_16x16x32_bf16 v[128:131], v[144:147], v[184:187], v[128:131]
	v_mfma_f32_16x16x32_bf16 v[112:115], v[136:139], v[192:195], v[112:115]
	v_mfma_f32_16x16x32_bf16 v[108:111], v[144:147], v[192:195], v[108:111]
	v_mfma_f32_16x16x32_bf16 v[96:99], v[136:139], v[200:203], v[96:99]
	v_mfma_f32_16x16x32_bf16 v[92:95], v[144:147], v[200:203], v[92:95]
	v_mfma_f32_16x16x32_bf16 v[80:83], v[136:139], v[208:211], v[80:83]
	v_mfma_f32_16x16x32_bf16 v[76:79], v[144:147], v[208:211], v[76:79]
	s_setprio 0
	s_setprio 1
	v_mfma_f32_16x16x32_bf16 v[120:123], v[148:151], v[174:177], v[120:123]
	v_mfma_f32_16x16x32_bf16 v[116:119], v[156:159], v[174:177], v[116:119]
	v_mfma_f32_16x16x32_bf16 v[104:107], v[148:151], v[188:191], v[104:107]
	v_mfma_f32_16x16x32_bf16 v[100:103], v[156:159], v[188:191], v[100:103]
	v_mfma_f32_16x16x32_bf16 v[88:91], v[148:151], v[196:199], v[88:91]
	v_mfma_f32_16x16x32_bf16 v[84:87], v[156:159], v[196:199], v[84:87]
	v_mfma_f32_16x16x32_bf16 v[72:75], v[148:151], v[204:207], v[72:75]
	v_mfma_f32_16x16x32_bf16 v[68:71], v[156:159], v[204:207], v[68:71]
	v_mfma_f32_16x16x32_bf16 v[120:123], v[152:155], v[184:187], v[120:123]
	v_mfma_f32_16x16x32_bf16 v[116:119], v[170:173], v[184:187], v[116:119]
	v_mfma_f32_16x16x32_bf16 v[104:107], v[152:155], v[192:195], v[104:107]
	v_mfma_f32_16x16x32_bf16 v[100:103], v[170:173], v[192:195], v[100:103]
	v_mfma_f32_16x16x32_bf16 v[88:91], v[152:155], v[200:203], v[88:91]
	v_mfma_f32_16x16x32_bf16 v[84:87], v[170:173], v[200:203], v[84:87]
	v_mfma_f32_16x16x32_bf16 v[72:75], v[152:155], v[208:211], v[72:75]
	v_mfma_f32_16x16x32_bf16 v[68:71], v[170:173], v[208:211], v[68:71]
	s_barrier
	s_setprio 0
	s_add_i32 s31, s67, s50
	v_lshl_add_u64 v[178:179], s[44:45], 0, v[2:3]
	s_mov_b32 m0, s31
	ds_read_b128 v[174:177], v183 offset:16384
	ds_read_b128 v[184:187], v183 offset:17408
	ds_read_b128 v[188:191], v183 offset:18432
	ds_read_b128 v[192:195], v183 offset:19456
	ds_read_b128 v[196:199], v183 offset:20480
	ds_read_b128 v[200:203], v183 offset:21504
	ds_read_b128 v[204:207], v183 offset:22528
	ds_read_b128 v[208:211], v183 offset:23552
	global_load_lds_dwordx4 v[178:179], off
	s_add_i32 m0, s31, 0x2000
	s_add_u32 s68, s44, 0x200000
	v_lshl_add_u64 v[212:213], s[44:45], 0, v[160:161]
	s_addc_u32 s69, s45, 0
	s_add_i32 s26, s26, s50
	global_load_lds_dwordx4 v[212:213], off
	v_lshl_add_u64 v[214:215], s[68:69], 0, v[2:3]
	s_mov_b32 m0, s26
	v_lshl_add_u64 v[216:217], s[46:47], 0, v[162:163]
	global_load_lds_dwordx4 v[214:215], off
	v_lshl_add_u64 v[214:215], s[68:69], 0, v[160:161]
	s_add_i32 m0, s26, 0x2000
	s_nop 0
	global_load_lds_dwordx4 v[214:215], off
	v_lshl_add_u64 v[214:215], s[46:47], 0, v[164:165]
	s_mov_b32 m0, s51
	s_nop 0
	global_load_lds_dwordx4 v[214:215], off
	s_mov_b32 m0, s52
	s_nop 0
	global_load_lds_dwordx4 v[216:217], off
	s_waitcnt vmcnt(8)
	s_waitcnt lgkmcnt(0)
	s_setprio 1
	s_barrier
; #define PG8_STAGE(bufoff, gbase, voff) do { _Pragma("unroll") for (int _i = 0; _i < 2; ++_i) \
;         __builtin_amdgcn_global_load_lds((const unsigned*)((const char*)(gbase) + (voff)[_i]), (PG8_LAS unsigned*)(lds + (bufoff) + ldsw + _i * 8192), 16, 0, 0); } while (0)
; #define PG8_LDA(dst, b, h) do { _Pragma("unroll") for (int m = 0; m < 4; ++m) _Pragma("unroll") for (int k = 0; k < 2; ++k) dst[m][k] = *(const PG8_LAS bf16x8*)(lds + PG8_SA(b, h) + aoff + m * 2048 + k * 1024); } while (0)
; #define PG8_LDB(dst, b, h) do { _Pragma("unroll") for (int n = 0; n < 2; ++n) _Pragma("unroll") for (int k = 0; k < 2; ++k) dst[n][k] = *(const PG8_LAS bf16x8*)(lds + PG8_SB(b, h) + boff + n * 2048 + k * 1024); } while (0)
; #define PG8_MMA(ai, bj, At, Bt) do { __builtin_amdgcn_s_setprio(1); _Pragma("unroll") for (int m = 0; m < 4; ++m) _Pragma("unroll") for (int n = 0; n < 2; ++n) _Pragma("unroll") for (int k = 0; k < 2; ++k) \
;         acc[ai][bj][m][n] = __builtin_amdgcn_mfma_f32_16x16x32_bf16(Bt[n][k], At[m][k], acc[ai][bj][m][n], 0, 0, 0); __builtin_amdgcn_s_setprio(0); } while (0)
; #define PG8_WAIT_V(n) asm volatile("s_waitcnt vmcnt(" #n ")" ::: "memory")
; #define PG8_WAIT_L(n) asm volatile("s_waitcnt lgkmcnt(" #n ")" ::: "memory")
; #define PG8_BAR __builtin_amdgcn_s_barrier()
; #define PG8_SCHED __builtin_amdgcn_sched_barrier(0)
; template <class Epi, class Sched, bool ALIGN_EPI = false, bool SP2 = false>
; __device__ __forceinline__ void gemm_phase(PG8_LAS unsigned char* lds, const Gemm g, const Sched& S, const Epi& E) {
;     ...
;             PG8_WAIT_V(8); PG8_WAIT_L(0); PG8_BAR; PG8_MMA(1, 0, At, B0); PG8_MMA(1, 1, At, B1); PG8_BAR; PG8_SCHED;
;             PG8_LDB(B0, 1, 0); PG8_LDB(B1, 1, 1); PG8_SCHED; PG8_LDA(At, 1, 0); PG8_STAGE(PG8_SA(0, 1), a2 + hstep, voffA);
;             PG8_WAIT_V(8); PG8_WAIT_L(0); PG8_BAR; PG8_MMA(0, 0, At, B0); PG8_MMA(0, 1, At, B1); PG8_BAR; PG8_SCHED;
	v_mfma_f32_16x16x32_bf16 v[64:67], v[124:127], v[174:177], v[64:67]
	v_mfma_f32_16x16x32_bf16 v[60:63], v[140:143], v[174:177], v[60:63]
	v_mfma_f32_16x16x32_bf16 v[48:51], v[124:127], v[188:191], v[48:51]
	v_mfma_f32_16x16x32_bf16 v[44:47], v[140:143], v[188:191], v[44:47]
	v_mfma_f32_16x16x32_bf16 v[32:35], v[124:127], v[196:199], v[32:35]
	v_mfma_f32_16x16x32_bf16 v[28:31], v[140:143], v[196:199], v[28:31]
	v_mfma_f32_16x16x32_bf16 v[16:19], v[124:127], v[204:207], v[16:19]
	v_mfma_f32_16x16x32_bf16 v[12:15], v[140:143], v[204:207], v[12:15]
	v_mfma_f32_16x16x32_bf16 v[64:67], v[136:139], v[184:187], v[64:67]
	v_mfma_f32_16x16x32_bf16 v[60:63], v[144:147], v[184:187], v[60:63]
	v_mfma_f32_16x16x32_bf16 v[48:51], v[136:139], v[192:195], v[48:51]
	v_mfma_f32_16x16x32_bf16 v[44:47], v[144:147], v[192:195], v[44:47]
	v_mfma_f32_16x16x32_bf16 v[32:35], v[136:139], v[200:203], v[32:35]
	v_mfma_f32_16x16x32_bf16 v[28:31], v[144:147], v[200:203], v[28:31]
	v_mfma_f32_16x16x32_bf16 v[16:19], v[136:139], v[208:211], v[16:19]
	v_mfma_f32_16x16x32_bf16 v[12:15], v[144:147], v[208:211], v[12:15]
	s_setprio 0
	s_setprio 1
	v_mfma_f32_16x16x32_bf16 v[56:59], v[148:151], v[174:177], v[56:59]
	v_mfma_f32_16x16x32_bf16 v[52:55], v[156:159], v[174:177], v[52:55]
	v_mfma_f32_16x16x32_bf16 v[40:43], v[148:151], v[188:191], v[40:43]
	v_mfma_f32_16x16x32_bf16 v[36:39], v[156:159], v[188:191], v[36:39]
	v_mfma_f32_16x16x32_bf16 v[24:27], v[148:151], v[196:199], v[24:27]
	v_mfma_f32_16x16x32_bf16 v[20:23], v[156:159], v[196:199], v[20:23]
	v_mfma_f32_16x16x32_bf16 v[8:11], v[148:151], v[204:207], v[8:11]
	v_mfma_f32_16x16x32_bf16 v[4:7], v[156:159], v[204:207], v[4:7]
	v_mfma_f32_16x16x32_bf16 v[56:59], v[152:155], v[184:187], v[56:59]
	v_mfma_f32_16x16x32_bf16 v[52:55], v[170:173], v[184:187], v[52:55]
	v_mfma_f32_16x16x32_bf16 v[40:43], v[152:155], v[192:195], v[40:43]
	v_mfma_f32_16x16x32_bf16 v[36:39], v[170:173], v[192:195], v[36:39]
	v_mfma_f32_16x16x32_bf16 v[24:27], v[152:155], v[200:203], v[24:27]
	v_mfma_f32_16x16x32_bf16 v[20:23], v[170:173], v[200:203], v[20:23]
	v_mfma_f32_16x16x32_bf16 v[8:11], v[152:155], v[208:211], v[8:11]
	v_mfma_f32_16x16x32_bf16 v[4:7], v[170:173], v[208:211], v[4:7]
	s_barrier
	s_setprio 0
	s_add_i32 s26, 0, 0x18000
	s_add_i32 s31, 0, 0x1c000
	v_add_u32_e32 v144, s26, v181
	v_add_u32_e32 v170, s31, v181
	ds_read_b128 v[124:127], v144
	ds_read_b128 v[136:139], v144 offset:1024
	ds_read_b128 v[140:143], v144 offset:2048
	ds_read_b128 v[144:147], v144 offset:3072
	ds_read_b128 v[148:151], v170
	ds_read_b128 v[152:155], v170 offset:1024
	ds_read_b128 v[156:159], v170 offset:2048
	ds_read_b128 v[170:173], v170 offset:3072
	s_add_u32 s46, s46, 0x200000
	s_addc_u32 s47, s47, 0
	s_mov_b32 m0, s53
	v_lshl_add_u64 v[218:219], s[46:47], 0, v[164:165]
	ds_read_b128 v[174:177], v183 offset:32768
	ds_read_b128 v[184:187], v183 offset:33792
	ds_read_b128 v[188:191], v183 offset:34816
	ds_read_b128 v[192:195], v183 offset:35840
	ds_read_b128 v[196:199], v183 offset:36864
	ds_read_b128 v[200:203], v183 offset:37888
	ds_read_b128 v[204:207], v183 offset:38912
	ds_read_b128 v[208:211], v183 offset:39936
	global_load_lds_dwordx4 v[218:219], off
	v_lshl_add_u64 v[218:219], s[46:47], 0, v[162:163]
	s_mov_b32 m0, s54
	s_nop 0
	global_load_lds_dwordx4 v[218:219], off
	s_waitcnt vmcnt(8)
	s_waitcnt lgkmcnt(0)
	s_setprio 1
	s_barrier
	v_mfma_f32_16x16x32_bf16 v[132:135], v[124:127], v[174:177], v[132:135]
	v_mfma_f32_16x16x32_bf16 v[128:131], v[140:143], v[174:177], v[128:131]
	v_mfma_f32_16x16x32_bf16 v[112:115], v[124:127], v[188:191], v[112:115]
	v_mfma_f32_16x16x32_bf16 v[108:111], v[140:143], v[188:191], v[108:111]
	v_mfma_f32_16x16x32_bf16 v[96:99], v[124:127], v[196:199], v[96:99]
	v_mfma_f32_16x16x32_bf16 v[92:95], v[140:143], v[196:199], v[92:95]
	v_mfma_f32_16x16x32_bf16 v[80:83], v[124:127], v[204:207], v[80:83]
	v_mfma_f32_16x16x32_bf16 v[76:79], v[140:143], v[204:207], v[76:79]
	v_mfma_f32_16x16x32_bf16 v[132:135], v[136:139], v[184:187], v[132:135]
	v_mfma_f32_16x16x32_bf16 v[128:131], v[144:147], v[184:187], v[128:131]
	v_mfma_f32_16x16x32_bf16 v[112:115], v[136:139], v[192:195], v[112:115]
	v_mfma_f32_16x16x32_bf16 v[108:111], v[144:147], v[192:195], v[108:111]
	v_mfma_f32_16x16x32_bf16 v[96:99], v[136:139], v[200:203], v[96:99]
	v_mfma_f32_16x16x32_bf16 v[92:95], v[144:147], v[200:203], v[92:95]
	v_mfma_f32_16x16x32_bf16 v[80:83], v[136:139], v[208:211], v[80:83]
	v_mfma_f32_16x16x32_bf16 v[76:79], v[144:147], v[208:211], v[76:79]
	s_setprio 0
	s_setprio 1
	v_mfma_f32_16x16x32_bf16 v[120:123], v[148:151], v[174:177], v[120:123]
	v_mfma_f32_16x16x32_bf16 v[116:119], v[156:159], v[174:177], v[116:119]
	v_mfma_f32_16x16x32_bf16 v[104:107], v[148:151], v[188:191], v[104:107]
	v_mfma_f32_16x16x32_bf16 v[100:103], v[156:159], v[188:191], v[100:103]
	v_mfma_f32_16x16x32_bf16 v[88:91], v[148:151], v[196:199], v[88:91]
	v_mfma_f32_16x16x32_bf16 v[84:87], v[156:159], v[196:199], v[84:87]
	v_mfma_f32_16x16x32_bf16 v[72:75], v[148:151], v[204:207], v[72:75]
	v_mfma_f32_16x16x32_bf16 v[68:71], v[156:159], v[204:207], v[68:71]
	v_mfma_f32_16x16x32_bf16 v[120:123], v[152:155], v[184:187], v[120:123]
	v_mfma_f32_16x16x32_bf16 v[116:119], v[170:173], v[184:187], v[116:119]
	v_mfma_f32_16x16x32_bf16 v[104:107], v[152:155], v[192:195], v[104:107]
	v_mfma_f32_16x16x32_bf16 v[100:103], v[170:173], v[192:195], v[100:103]
	v_mfma_f32_16x16x32_bf16 v[88:91], v[152:155], v[200:203], v[88:91]
	v_mfma_f32_16x16x32_bf16 v[84:87], v[170:173], v[200:203], v[84:87]
	v_mfma_f32_16x16x32_bf16 v[72:75], v[152:155], v[208:211], v[72:75]
	v_mfma_f32_16x16x32_bf16 v[68:71], v[170:173], v[208:211], v[68:71]
	s_barrier
; #define PG8_STAGE(bufoff, gbase, voff) do { _Pragma("unroll") for (int _i = 0; _i < 2; ++_i) \
;         __builtin_amdgcn_global_load_lds((const unsigned*)((const char*)(gbase) + (voff)[_i]), (PG8_LAS unsigned*)(lds + (bufoff) + ldsw + _i * 8192), 16, 0, 0); } while (0)
; #define PG8_LDA(dst, b, h) do { _Pragma("unroll") for (int m = 0; m < 4; ++m) _Pragma("unroll") for (int k = 0; k < 2; ++k) dst[m][k] = *(const PG8_LAS bf16x8*)(lds + PG8_SA(b, h) + aoff + m * 2048 + k * 1024); } while (0)
; #define PG8_MMA(ai, bj, At, Bt) do { __builtin_amdgcn_s_setprio(1); _Pragma("unroll") for (int m = 0; m < 4; ++m) _Pragma("unroll") for (int n = 0; n < 2; ++n) _Pragma("unroll") for (int k = 0; k < 2; ++k) \
;         acc[ai][bj][m][n] = __builtin_amdgcn_mfma_f32_16x16x32_bf16(Bt[n][k], At[m][k], acc[ai][bj][m][n], 0, 0, 0); __builtin_amdgcn_s_setprio(0); } while (0)
; #define PG8_WAIT_V(n) asm volatile("s_waitcnt vmcnt(" #n ")" ::: "memory")
; #define PG8_WAIT_L(n) asm volatile("s_waitcnt lgkmcnt(" #n ")" ::: "memory")
; #define PG8_BAR __builtin_amdgcn_s_barrier()
; #define PG8_SCHED __builtin_amdgcn_sched_barrier(0)
; template <class Epi, class Sched, bool ALIGN_EPI = false, bool SP2 = false>
; __device__ __forceinline__ void gemm_phase(PG8_LAS unsigned char* lds, const Gemm g, const Sched& S, const Epi& E) {
;     ...
;         for (int t = 0; t < nt; t += 2) {
;             const bool last = (t == nt - 2);
;             const char* a1 = cA + (size_t)(t + 1) * kstep;
;             const char* a2 = last ? nA : cA + (size_t)(t + 2) * kstep; const char* b2 = last ? nB : cB + (size_t)(t + 2) * kstep;
;     ...
;             PG8_LDA(At, 1, 1); PG8_STAGE(PG8_SB(1, 0), b3, voffB); PG8_STAGE(PG8_SB(1, 1), b3 + hstep, voffB); PG8_STAGE(PG8_SA(1, 0), a3, voffA);
;             PG8_WAIT_V(8); PG8_WAIT_L(0); PG8_BAR; PG8_MMA(1, 0, At, B0); PG8_MMA(1, 1, At, B1); PG8_BAR; PG8_SCHED;
	s_setprio 0
	s_add_i32 s26, s26, s50
	v_lshl_add_u64 v[178:179], v[178:179], 0, s[60:61]
	s_mov_b32 m0, s26
	ds_read_b128 v[174:177], v183 offset:49152
	ds_read_b128 v[184:187], v183 offset:50176
	ds_read_b128 v[188:191], v183 offset:51200
	ds_read_b128 v[192:195], v183 offset:52224
	ds_read_b128 v[196:199], v183 offset:53248
	ds_read_b128 v[200:203], v183 offset:54272
	ds_read_b128 v[204:207], v183 offset:55296
	ds_read_b128 v[208:211], v183 offset:56320
	global_load_lds_dwordx4 v[178:179], off
	s_add_i32 m0, s26, 0x2000
	s_add_u32 s44, s44, 0x200080
	v_lshl_add_u64 v[178:179], v[212:213], 0, s[60:61]
	s_addc_u32 s45, s45, 0
	s_add_i32 s26, s31, s50
	global_load_lds_dwordx4 v[178:179], off
	v_lshl_add_u64 v[178:179], s[44:45], 0, v[2:3]
	s_mov_b32 m0, s26
	s_nop 0
	global_load_lds_dwordx4 v[178:179], off
	v_lshl_add_u64 v[178:179], s[44:45], 0, v[160:161]
	s_add_i32 m0, s26, 0x2000
	s_nop 0
	global_load_lds_dwordx4 v[178:179], off
	v_lshl_add_u64 v[178:179], v[214:215], 0, s[60:61]
	s_mov_b32 m0, s56
	s_nop 0
	global_load_lds_dwordx4 v[178:179], off
	v_lshl_add_u64 v[178:179], v[216:217], 0, s[60:61]
	s_mov_b32 m0, s57
	s_nop 0
	global_load_lds_dwordx4 v[178:179], off
	s_waitcnt vmcnt(8)
	s_waitcnt lgkmcnt(0)
	s_setprio 1
	s_barrier
	v_mfma_f32_16x16x32_bf16 v[64:67], v[124:127], v[174:177], v[64:67]
	v_mfma_f32_16x16x32_bf16 v[60:63], v[140:143], v[174:177], v[60:63]
	v_mfma_f32_16x16x32_bf16 v[48:51], v[124:127], v[188:191], v[48:51]
	v_mfma_f32_16x16x32_bf16 v[44:47], v[140:143], v[188:191], v[44:47]
	v_mfma_f32_16x16x32_bf16 v[32:35], v[124:127], v[196:199], v[32:35]
	v_mfma_f32_16x16x32_bf16 v[28:31], v[140:143], v[196:199], v[28:31]
	v_mfma_f32_16x16x32_bf16 v[16:19], v[124:127], v[204:207], v[16:19]
	v_mfma_f32_16x16x32_bf16 v[12:15], v[140:143], v[204:207], v[12:15]
	v_mfma_f32_16x16x32_bf16 v[64:67], v[136:139], v[184:187], v[64:67]
	v_mfma_f32_16x16x32_bf16 v[60:63], v[144:147], v[184:187], v[60:63]
	v_mfma_f32_16x16x32_bf16 v[48:51], v[136:139], v[192:195], v[48:51]
	v_mfma_f32_16x16x32_bf16 v[44:47], v[144:147], v[192:195], v[44:47]
	v_mfma_f32_16x16x32_bf16 v[32:35], v[136:139], v[200:203], v[32:35]
	v_mfma_f32_16x16x32_bf16 v[28:31], v[144:147], v[200:203], v[28:31]
	v_mfma_f32_16x16x32_bf16 v[16:19], v[136:139], v[208:211], v[16:19]
	v_mfma_f32_16x16x32_bf16 v[12:15], v[144:147], v[208:211], v[12:15]
	s_setprio 0
	s_setprio 1
	v_mfma_f32_16x16x32_bf16 v[56:59], v[148:151], v[174:177], v[56:59]
	v_mfma_f32_16x16x32_bf16 v[52:55], v[156:159], v[174:177], v[52:55]
	v_mfma_f32_16x16x32_bf16 v[40:43], v[148:151], v[188:191], v[40:43]
	v_mfma_f32_16x16x32_bf16 v[36:39], v[156:159], v[188:191], v[36:39]
	v_mfma_f32_16x16x32_bf16 v[24:27], v[148:151], v[196:199], v[24:27]
	v_mfma_f32_16x16x32_bf16 v[20:23], v[156:159], v[196:199], v[20:23]
	v_mfma_f32_16x16x32_bf16 v[8:11], v[148:151], v[204:207], v[8:11]
	v_mfma_f32_16x16x32_bf16 v[4:7], v[156:159], v[204:207], v[4:7]
	v_mfma_f32_16x16x32_bf16 v[56:59], v[152:155], v[184:187], v[56:59]
	v_mfma_f32_16x16x32_bf16 v[52:55], v[170:173], v[184:187], v[52:55]
	v_mfma_f32_16x16x32_bf16 v[40:43], v[152:155], v[192:195], v[40:43]
	v_mfma_f32_16x16x32_bf16 v[36:39], v[170:173], v[192:195], v[36:39]
	v_mfma_f32_16x16x32_bf16 v[24:27], v[152:155], v[200:203], v[24:27]
	v_mfma_f32_16x16x32_bf16 v[20:23], v[170:173], v[200:203], v[20:23]
	v_mfma_f32_16x16x32_bf16 v[8:11], v[152:155], v[208:211], v[8:11]
	v_mfma_f32_16x16x32_bf16 v[4:7], v[170:173], v[208:211], v[4:7]
	s_barrier
	s_setprio 0
	s_add_i32 s74, s74, 2
	s_add_u32 s6, s6, 0x100
	s_addc_u32 s7, s7, 0
	s_add_u32 s66, s66, 0x100
	s_addc_u32 s70, s70, 0
	s_cmpk_gt_u32 s74, 0x7d
	s_cbranch_scc0 .LBB0_2176
	s_and_b64 vcc, exec, s[18:19]
	s_cbranch_vccz .LBB0_2179
	s_barrier
